# prefetch all per-token row loads at loop top in mixer prep (counted vmcnt); hoist loop-invariant norm-gain loads out of the residual/rmsnorm row loops
# speedup vs baseline: 1.0373x; 1.0260x over previous
; __device__ __forceinline__ void phase_rowwise(const bf16_t* ysrc, const float* hin, float* hout, float wt, const float* g_post, const float* g_pre, bf16_t* xn) {
;     PHASE_IDS;
;     for (int row = gw; row < T; row += 2 * ngw) {
;         const int rowb = row + ngw; const bool two = rowb < T; const int rb = two ? rowb : row;
;         f32x4 ha[4], hb[4]; v2u ya[4], yb[4];
;         { const f32x4* hr = (const f32x4*)(hin + (size_t)row * DM) + lane; const f32x4* hr2 = (const f32x4*)(hin + (size_t)rb * DM) + lane;
;     ...
;                 for (int j = 0; j < 4; ++j) { const f32x4 g = *((const f32x4*)g_post + lane + 64 * j); h[j] = h[j] + y[j] * g * rinv; }
;     ...
;                 for (int j = 0; j < 4; ++j) { const f32x4 g = *((const f32x4*)g_pre + lane + 64 * j); const f32x4 v = h[j] * g * rinv;
.LBB0_263:
	s_mov_b32 s5, s51
	s_mov_b32 s4, s50
	s_mov_b32 s14, s51
	s_mov_b32 s15, s50
	v_mov_b32_e32 v0, v185
	s_nop 0
	v_readfirstlane_b32 s6, v0
	s_ashr_i32 s8, s6, 6
	v_readlane_b32 s6, v253, 7
	s_add_i32 s18, s8, s6
	s_cmpk_gt_i32 s18, 0x3fff
	s_cbranch_scc1 .LBB0_271
	v_and_b32_e32 v2, 63, v0
	v_lshlrev_b32_e32 v36, 3, v2
	v_mov_b32_e32 v37, v1
	v_lshlrev_b32_e32 v0, 4, v2
	v_lshl_add_u64 v[2:3], s[4:5], 0, v[36:37]
	s_mov_b64 s[6:7], 0x12e00000
	v_lshl_add_u64 v[38:39], v[2:3], 0, s[6:7]
	v_readlane_b32 s6, v254, 21
	v_readlane_b32 s7, v254, 22
	v_and_b32_e32 v2, 64, v241
	v_add_u32_e32 v2, 64, v2
	v_lshl_add_u64 v[40:41], s[6:7], 0, v[0:1]
	v_readlane_b32 s6, v254, 19
	v_readlane_b32 s7, v254, 20
	v_xor_b32_e32 v3, 1, v241
	v_cmp_lt_i32_e32 vcc, v3, v2
	v_lshl_add_u64 v[42:43], s[6:7], 0, v[0:1]
	s_ashr_i32 s6, s8, 31
	v_readlane_b32 s7, v253, 7
	s_add_u32 s10, s7, s8
	v_readlane_b32 s7, v253, 6
	s_addc_u32 s11, s7, s6
	v_cndmask_b32_e32 v3, v241, v3, vcc
	s_lshl_b64 s[6:7], s[10:11], 12
	v_lshlrev_b32_e32 v72, 2, v3
	v_xor_b32_e32 v3, 2, v241
	s_add_u32 s6, s48, s6
	v_readlane_b32 s9, v253, 8
	v_cmp_lt_i32_e32 vcc, v3, v2
	s_addc_u32 s7, s49, s7
	s_add_i32 s12, s9, s8
	v_cndmask_b32_e32 v3, v241, v3, vcc
	s_ashr_i32 s13, s12, 31
	v_lshlrev_b32_e32 v73, 2, v3
	v_xor_b32_e32 v3, 4, v241
	s_lshl_b64 s[8:9], s[12:13], 11
	v_cmp_lt_i32_e32 vcc, v3, v2
	s_add_u32 s8, s15, s8
	s_addc_u32 s9, s14, s9
	v_cndmask_b32_e32 v3, v241, v3, vcc
	s_lshl_b64 s[16:17], s[10:11], 11
	v_lshlrev_b32_e32 v74, 2, v3
	v_xor_b32_e32 v3, 8, v241
	s_add_u32 s4, s4, s16
	v_cmp_lt_i32_e32 vcc, v3, v2
	s_addc_u32 s5, s5, s17
	s_add_u32 s10, s4, 0x12e00400
	v_cndmask_b32_e32 v3, v241, v3, vcc
	v_lshlrev_b32_e32 v75, 2, v3
	v_xor_b32_e32 v3, 16, v241
	s_addc_u32 s11, s5, 0
	s_lshl_b64 s[4:5], s[12:13], 12
	v_cmp_lt_i32_e32 vcc, v3, v2
	s_add_u32 s12, s48, s4
	s_addc_u32 s13, s49, s5
	v_cndmask_b32_e32 v3, v241, v3, vcc
	v_lshlrev_b32_e32 v76, 2, v3
	v_xor_b32_e32 v3, 32, v241
	s_add_u32 s4, s15, s16
	v_cmp_lt_i32_e32 vcc, v3, v2
	s_addc_u32 s5, s14, s17
	s_add_u32 s14, s4, 0x16e00400
	v_cndmask_b32_e32 v2, v241, v3, vcc
	v_lshl_add_u64 v[34:35], s[48:49], 0, v[0:1]
	v_lshlrev_b32_e32 v77, 2, v2
	s_addc_u32 s15, s5, 0
	global_load_dwordx4 v[140:143], v[40:41], off
	global_load_dwordx4 v[144:147], v[40:41], off offset:1024
	global_load_dwordx4 v[148:151], v[40:41], off offset:2048
	global_load_dwordx4 v[152:155], v[40:41], off offset:3072
	v_readlane_b32 s20, v252, 26
	v_readlane_b32 s21, v252, 27
	s_nop 3
	s_andn2_b64 vcc, exec, s[20:21]
	s_cbranch_vccnz .Lrw_nopre_0
	global_load_dwordx4 v[156:159], v[42:43], off
	global_load_dwordx4 v[160:163], v[42:43], off offset:1024
	global_load_dwordx4 v[164:167], v[42:43], off offset:2048
	global_load_dwordx4 v[168:171], v[42:43], off offset:3072
.Lrw_nopre_0:
	s_waitcnt vmcnt(0)
	s_branch .LBB0_266

; __device__ __forceinline__ float bflo(unsigned w) { return __uint_as_float(w << 16); }
; __device__ __forceinline__ float bfhi(unsigned w) { return __uint_as_float(w & 0xffff0000u); }
; __device__ __forceinline__ float bflo(unsigned w) { return __uint_as_float(w << 16); }
; __device__ __forceinline__ float bfhi(unsigned w) { return __uint_as_float(w & 0xffff0000u); }
; __device__ __forceinline__ void phase_rowwise(const bf16_t* ysrc, const float* hin, float* hout, float wt, const float* g_post, const float* g_pre, bf16_t* xn) {
;     ...
;     for (int row = gw; row < T; row += 2 * ngw) {
;         const int rowb = row + ngw; const bool two = rowb < T; const int rb = two ? rowb : row;
;         f32x4 ha[4], hb[4]; v2u ya[4], yb[4];
;         { const f32x4* hr = (const f32x4*)(hin + (size_t)row * DM) + lane; const f32x4* hr2 = (const f32x4*)(hin + (size_t)rb * DM) + lane;
; #pragma unroll
;           for (int j = 0; j < 4; ++j) { ha[j] = hr[64 * j]; hb[j] = hr2[64 * j]; }
;           if (ysrc) { const v2u* yr = (const v2u*)(ysrc + (size_t)row * DM) + lane; const v2u* yr2 = (const v2u*)(ysrc + (size_t)rb * DM) + lane;
; #pragma unroll
;             for (int j = 0; j < 4; ++j) { ya[j] = yr[64 * j]; yb[j] = yr2[64 * j]; } } }
; #pragma unroll
;         for (int half = 0; half < 2; ++half) {
;             if (half == 1 && !two) break;
;             const int r = half ? rowb : row;
;             f32x4 h[4];
; #pragma unroll
;             for (int j = 0; j < 4; ++j) h[j] = half ? hb[j] : ha[j];
;             if (ysrc) {
;                 f32x4 y[4]; float s = 0.f;
; #pragma unroll
;                 for (int j = 0; j < 4; ++j) { const v2u w = half ? yb[j] : ya[j]; y[j] = (f32x4){bflo(w.x), bfhi(w.x), bflo(w.y), bfhi(w.y)}; s += (y[j].x * y[j].x + y[j].y * y[j].y) + (y[j].z * y[j].z + y[j].w * y[j].w); }
;                 const float rinv = wt * rsqrtf(wave_sum(s) * (1.f / DM) + NORM_EPS);
; #pragma unroll
;                 for (int j = 0; j < 4; ++j) { const f32x4 g = *((const f32x4*)g_post + lane + 64 * j); h[j] = h[j] + y[j] * g * rinv; }
;             }
;             f32x4* ho = (f32x4*)(hout + (size_t)r * DM) + lane;
; #pragma unroll
;             for (int j = 0; j < 4; ++j) ho[64 * j] = h[j];
.LBB0_266:
	s_add_i32 s19, s24, s18
	s_cmpk_lt_i32 s19, 0x4000
	s_cselect_b64 s[16:17], -1, 0
	s_and_b64 s[4:5], s[16:17], exec
	s_cselect_b32 s4, s19, s18
	s_ashr_i32 s5, s4, 31
	s_lshl_b64 s[20:21], s[4:5], 12
	v_lshl_add_u64 v[52:53], s[6:7], 0, v[0:1]
	v_lshl_add_u64 v[2:3], v[34:35], 0, s[20:21]
	v_lshl_add_u64 v[48:49], s[10:11], 0, v[36:37]
	s_lshl_b64 s[4:5], s[4:5], 11
	global_load_dwordx4 v[18:21], v[52:53], off
	global_load_dwordx4 v[14:17], v[2:3], off
	global_load_dwordx4 v[22:25], v[52:53], off offset:1024
	global_load_dwordx4 v[10:13], v[2:3], off offset:1024
	global_load_dwordx4 v[26:29], v[52:53], off offset:2048
	global_load_dwordx4 v[6:9], v[2:3], off offset:2048
	global_load_dwordx4 v[30:33], v[52:53], off offset:3072
	s_nop 0
	global_load_dwordx4 v[2:5], v[2:3], off offset:3072
	v_lshl_add_u64 v[54:55], v[38:39], 0, s[4:5]
	global_load_dwordx2 v[56:57], v[48:49], off offset:-1024
	global_load_dwordx2 v[50:51], v[54:55], off
	global_load_dwordx2 v[58:59], v[48:49], off offset:-512
	global_load_dwordx2 v[46:47], v[54:55], off offset:512
	global_load_dwordx2 v[62:63], v[48:49], off
	global_load_dwordx2 v[44:45], v[54:55], off offset:1024
	global_load_dwordx2 v[78:79], v[48:49], off offset:512
	s_nop 0
	global_load_dwordx2 v[48:49], v[54:55], off offset:1536
	v_readlane_b32 s20, v252, 26
	v_readlane_b32 s21, v252, 27
	s_waitcnt vmcnt(7)
	v_and_b32_e32 v71, 0xffff0000, v57
	v_and_b32_e32 v69, 0xffff0000, v56
	v_lshlrev_b32_e32 v70, 16, v57
	v_mul_f32_e32 v54, v71, v71
	s_waitcnt vmcnt(5)
	v_and_b32_e32 v67, 0xffff0000, v59
	v_and_b32_e32 v66, 0xffff0000, v58
	v_lshlrev_b32_e32 v68, 16, v56
	v_pk_fma_f32 v[80:81], v[70:71], v[70:71], v[54:55] op_sel_hi:[1,1,0]
	v_lshlrev_b32_e32 v65, 16, v59
	v_lshlrev_b32_e32 v64, 16, v58
	v_pk_mul_f32 v[54:55], v[66:67], v[66:67]
	s_waitcnt vmcnt(1)
	v_and_b32_e32 v57, 0xffff0000, v78
	v_mul_f32_e32 v56, v69, v69
	v_pk_fma_f32 v[82:83], v[64:65], v[64:65], v[54:55]
	v_lshlrev_b32_e32 v59, 16, v78
	v_lshlrev_b32_e32 v54, 16, v79
	v_and_b32_e32 v55, 0xffff0000, v79
	v_pk_fma_f32 v[78:79], v[68:69], v[68:69], v[56:57] op_sel_hi:[1,1,0]
	v_mov_b32_e32 v84, v80
	v_mov_b32_e32 v58, v78
	v_mov_b32_e32 v85, v59
	v_pk_add_f32 v[78:79], v[78:79], v[80:81]
	v_pk_mul_f32 v[80:81], v[58:59], v[84:85]
	v_and_b32_e32 v61, 0xffff0000, v62
	v_mul_f32_e32 v86, v57, v57
	v_mov_b32_e32 v79, v81
	v_pk_add_f32 v[80:81], v[82:83], v[82:83] op_sel:[0,1] op_sel_hi:[1,0]
	v_lshlrev_b32_e32 v60, 16, v62
	v_lshlrev_b32_e32 v62, 16, v63
	v_and_b32_e32 v63, 0xffff0000, v63
	v_mov_b32_e32 v81, v86
	v_mul_f32_e32 v56, v61, v61
	v_pk_add_f32 v[78:79], v[78:79], v[80:81]
	v_pk_fma_f32 v[80:81], v[60:61], v[60:61], v[56:57] op_sel_hi:[1,1,0]
	v_mul_f32_e32 v56, v63, v63
	v_mul_f32_e32 v87, v54, v54
	v_mul_f32_e32 v88, v55, v55
	v_pk_fma_f32 v[82:83], v[62:63], v[62:63], v[56:57] op_sel_hi:[1,1,0]
	v_mov_b32_e32 v81, v87
	v_mov_b32_e32 v83, v88
	v_pk_add_f32 v[80:81], v[80:81], v[82:83]
	s_nop 0
	v_pk_add_f32 v[78:79], v[78:79], v[80:81]
	s_nop 0
	v_add_f32_e32 v56, v78, v79
	v_mov_b64_e32 v[78:79], v[140:141]
	v_mov_b64_e32 v[80:81], v[142:143]
	ds_bpermute_b32 v58, v72, v56
	s_waitcnt lgkmcnt(0)
	v_add_f32_e32 v56, v56, v58
	ds_bpermute_b32 v58, v73, v56
	s_waitcnt lgkmcnt(0)
	v_add_f32_e32 v56, v56, v58
	ds_bpermute_b32 v58, v74, v56
	s_waitcnt lgkmcnt(0)
	v_add_f32_e32 v56, v56, v58
	ds_bpermute_b32 v58, v75, v56
	s_waitcnt lgkmcnt(0)
	v_add_f32_e32 v56, v56, v58
	ds_bpermute_b32 v58, v76, v56
	s_waitcnt lgkmcnt(0)
	v_add_f32_e32 v56, v56, v58
	ds_bpermute_b32 v58, v77, v56
	s_waitcnt lgkmcnt(0)
	v_add_f32_e32 v56, v56, v58
	v_fmamk_f32 v56, v56, 0x3a800000, v184
	v_cmp_gt_f32_e32 vcc, s61, v56
	v_mul_f32_e32 v58, 0x4b800000, v56
	s_waitcnt vmcnt(0)
	v_pk_mul_f32 v[68:69], v[78:79], v[68:69]
	v_cndmask_b32_e32 v56, v56, v58, vcc
	v_rsq_f32_e32 v56, v56
	v_pk_mul_f32 v[70:71], v[80:81], v[70:71]
	v_mov_b32_e32 v79, v66
	v_mov_b32_e32 v66, v65
	v_mul_f32_e32 v58, 0x45800000, v56
	v_cndmask_b32_e32 v56, v56, v58, vcc
	v_mul_f32_e32 v58, 0.5, v56
	v_pk_fma_f32 v[20:21], v[70:71], v[58:59], v[20:21] op_sel_hi:[1,0,1]
	v_pk_fma_f32 v[18:19], v[68:69], v[58:59], v[18:19] op_sel_hi:[1,0,1]
	v_mov_b64_e32 v[68:69], v[144:145]
	v_mov_b64_e32 v[70:71], v[146:147]
	v_mov_b32_e32 v78, v64
	v_mov_b32_e32 v56, v59
	s_andn2_b64 vcc, exec, s[20:21]
	v_pk_mul_f32 v[64:65], v[70:71], v[66:67]
	s_nop 0
	v_pk_fma_f32 v[24:25], v[64:65], v[58:59], v[24:25] op_sel_hi:[1,0,1]
	v_mov_b64_e32 v[64:65], v[148:149]
	v_mov_b64_e32 v[66:67], v[150:151]
	v_pk_mul_f32 v[68:69], v[68:69], v[78:79]
	v_pk_mul_f32 v[60:61], v[64:65], v[60:61]
	v_pk_mul_f32 v[62:63], v[66:67], v[62:63]
	v_pk_fma_f32 v[26:27], v[60:61], v[58:59], v[26:27] op_sel_hi:[1,0,1]
	v_pk_fma_f32 v[28:29], v[62:63], v[58:59], v[28:29] op_sel_hi:[1,0,1]
	v_mov_b64_e32 v[60:61], v[152:153]
	v_mov_b64_e32 v[62:63], v[154:155]
	v_pk_fma_f32 v[22:23], v[68:69], v[58:59], v[22:23] op_sel_hi:[1,0,1]
	v_pk_mul_f32 v[56:57], v[56:57], v[60:61]
	v_pk_mul_f32 v[54:55], v[54:55], v[62:63]
	v_pk_fma_f32 v[30:31], v[56:57], v[58:59], v[30:31] op_sel_hi:[1,0,1]
	v_pk_fma_f32 v[32:33], v[54:55], v[58:59], v[32:33] op_sel_hi:[1,0,1]
	global_store_dwordx4 v[52:53], v[18:21], off
	global_store_dwordx4 v[52:53], v[22:25], off offset:1024
	global_store_dwordx4 v[52:53], v[26:29], off offset:2048
	global_store_dwordx4 v[52:53], v[30:33], off offset:3072
	v_cndmask_b32_e64 v52, 0, 1, s[20:21]
	v_cmp_ne_u32_e64 s[4:5], 1, v52
	s_cbranch_vccnz .LBB0_268
; __device__ __forceinline__ float bflo(unsigned w) { return __uint_as_float(w << 16); }
; __device__ __forceinline__ float bfhi(unsigned w) { return __uint_as_float(w & 0xffff0000u); }
; __device__ __forceinline__ unsigned pk2(float lo, float hi) { f32x2_t v = {lo, hi}; bf16x2_t b = __builtin_convertvector(v, bf16x2_t); return __builtin_bit_cast(unsigned, b); }
; __device__ __forceinline__ float bflo(unsigned w) { return __uint_as_float(w << 16); }
; __device__ __forceinline__ float bfhi(unsigned w) { return __uint_as_float(w & 0xffff0000u); }
; __device__ __forceinline__ void phase_rowwise(const bf16_t* ysrc, const float* hin, float* hout, float wt, const float* g_post, const float* g_pre, bf16_t* xn) {
;     ...
;             if (ysrc) {
;                 f32x4 y[4]; float s = 0.f;
; #pragma unroll
;                 for (int j = 0; j < 4; ++j) { const v2u w = half ? yb[j] : ya[j]; y[j] = (f32x4){bflo(w.x), bfhi(w.x), bflo(w.y), bfhi(w.y)}; s += (y[j].x * y[j].x + y[j].y * y[j].y) + (y[j].z * y[j].z + y[j].w * y[j].w); }
;                 const float rinv = wt * rsqrtf(wave_sum(s) * (1.f / DM) + NORM_EPS);
;     ...
;             if (g_pre) {
;                 float s = 0.f;
; #pragma unroll
;                 for (int j = 0; j < 4; ++j) s += (h[j].x * h[j].x + h[j].y * h[j].y) + (h[j].z * h[j].z + h[j].w * h[j].w);
;                 const float rinv = rsqrtf(wave_sum(s) * (1.f / DM) + NORM_EPS);
;                 unsigned long long* o8 = (unsigned long long*)(xn + (size_t)r * DM) + lane;
; #pragma unroll
;                 for (int j = 0; j < 4; ++j) { const f32x4 g = *((const f32x4*)g_pre + lane + 64 * j); const f32x4 v = h[j] * g * rinv;
;                     o8[64 * j] = (unsigned long long)pk2(v.x, v.y) | ((unsigned long long)pk2(v.z, v.w) << 32); }
	v_pk_mul_f32 v[52:53], v[20:21], v[20:21]
	v_pk_mul_f32 v[54:55], v[18:19], v[18:19]
	s_nop 0
	v_pk_mov_b32 v[56:57], v[54:55], v[52:53] op_sel:[1,0]
	v_mov_b32_e32 v55, v53
	v_pk_add_f32 v[52:53], v[56:57], v[54:55]
	v_pk_mul_f32 v[54:55], v[24:25], v[24:25]
	v_pk_add_f32 v[52:53], v[52:53], v[52:53] op_sel_hi:[0,1]
	v_pk_mul_f32 v[56:57], v[22:23], v[22:23]
	v_mul_f32_e32 v52, v26, v26
	v_pk_mov_b32 v[58:59], v[56:57], v[54:55] op_sel:[1,0]
	v_mov_b32_e32 v57, v55
	v_pk_add_f32 v[54:55], v[58:59], v[56:57]
	v_pk_fma_f32 v[56:57], v[26:27], v[26:27], v[52:53] op_sel_hi:[1,1,0]
	v_mul_f32_e32 v52, v28, v28
	v_pk_add_f32 v[54:55], v[54:55], v[54:55] op_sel_hi:[0,1]
	v_pk_fma_f32 v[58:59], v[28:29], v[28:29], v[52:53] op_sel_hi:[1,1,0]
	v_mul_f32_e32 v56, v30, v30
	v_mul_f32_e32 v58, v31, v31
	v_mul_f32_e32 v52, v32, v32
	v_mul_f32_e32 v54, v33, v33
	v_pk_add_f32 v[56:57], v[56:57], v[58:59]
	v_pk_add_f32 v[52:53], v[52:53], v[54:55]
	s_nop 0
	v_pk_add_f32 v[52:53], v[56:57], v[52:53]
	v_mov_b64_e32 v[56:57], v[156:157]
	v_mov_b64_e32 v[58:59], v[158:159]
	v_add_f32_e32 v52, v52, v53
	ds_bpermute_b32 v53, v72, v52
	s_waitcnt lgkmcnt(0)
	v_add_f32_e32 v52, v52, v53
	ds_bpermute_b32 v53, v73, v52
	s_waitcnt lgkmcnt(0)
	v_add_f32_e32 v52, v52, v53
	ds_bpermute_b32 v53, v74, v52
	s_waitcnt lgkmcnt(0)
	v_add_f32_e32 v52, v52, v53
	ds_bpermute_b32 v53, v75, v52
	s_waitcnt lgkmcnt(0)
	v_add_f32_e32 v52, v52, v53
	ds_bpermute_b32 v53, v76, v52
	s_waitcnt lgkmcnt(0)
	v_add_f32_e32 v52, v52, v53
	ds_bpermute_b32 v53, v77, v52
	s_waitcnt lgkmcnt(0)
	v_add_f32_e32 v52, v52, v53
	v_fmamk_f32 v52, v52, 0x3a800000, v184
	v_cmp_gt_f32_e32 vcc, s61, v52
	v_mul_f32_e32 v53, 0x4b800000, v52
	v_pk_mul_f32 v[20:21], v[20:21], v[58:59]
	v_cndmask_b32_e32 v52, v52, v53, vcc
	v_rsq_f32_e32 v52, v52
	v_pk_mul_f32 v[18:19], v[18:19], v[56:57]
	v_mul_f32_e32 v53, 0x45800000, v52
	v_cndmask_b32_e32 v54, v52, v53, vcc
	v_pk_mul_f32 v[20:21], v[20:21], v[54:55] op_sel_hi:[1,0]
	v_pk_mul_f32 v[18:19], v[18:19], v[54:55] op_sel_hi:[1,0]
	v_lshl_add_u64 v[52:53], s[14:15], 0, v[36:37]
	v_cvt_pk_bf16_f32 v18, v18, v19
	v_cvt_pk_bf16_f32 v19, v20, v21
	global_store_dwordx2 v[52:53], v[18:19], off offset:-1024
	v_mov_b64_e32 v[18:19], v[160:161]
	v_mov_b64_e32 v[20:21], v[162:163]
	v_pk_mul_f32 v[20:21], v[24:25], v[20:21]
	v_pk_mul_f32 v[18:19], v[22:23], v[18:19]
	v_pk_mul_f32 v[20:21], v[20:21], v[54:55] op_sel_hi:[1,0]
	v_pk_mul_f32 v[18:19], v[18:19], v[54:55] op_sel_hi:[1,0]
	s_nop 0
	v_cvt_pk_bf16_f32 v18, v18, v19
	v_cvt_pk_bf16_f32 v19, v20, v21
	global_store_dwordx2 v[52:53], v[18:19], off offset:-512
	v_mov_b64_e32 v[18:19], v[164:165]
	v_mov_b64_e32 v[20:21], v[166:167]
	v_pk_mul_f32 v[20:21], v[28:29], v[20:21]
	v_pk_mul_f32 v[18:19], v[26:27], v[18:19]
	v_pk_mul_f32 v[20:21], v[20:21], v[54:55] op_sel_hi:[1,0]
	v_pk_mul_f32 v[18:19], v[18:19], v[54:55] op_sel_hi:[1,0]
	s_nop 0
	v_cvt_pk_bf16_f32 v18, v18, v19
	v_cvt_pk_bf16_f32 v19, v20, v21
	global_store_dwordx2 v[52:53], v[18:19], off
	v_mov_b64_e32 v[18:19], v[168:169]
	v_mov_b64_e32 v[20:21], v[170:171]
	v_pk_mul_f32 v[20:21], v[32:33], v[20:21]
	v_pk_mul_f32 v[18:19], v[30:31], v[18:19]
	v_pk_mul_f32 v[20:21], v[20:21], v[54:55] op_sel_hi:[1,0]
	v_pk_mul_f32 v[18:19], v[18:19], v[54:55] op_sel_hi:[1,0]
	s_nop 0
	v_cvt_pk_bf16_f32 v18, v18, v19
	v_cvt_pk_bf16_f32 v19, v20, v21
	global_store_dwordx2 v[52:53], v[18:19], off offset:512
.LBB0_268:
	s_andn2_b64 vcc, exec, s[16:17]
	s_cbranch_vccnz .LBB0_265
	v_lshlrev_b32_e32 v32, 16, v50
	v_and_b32_e32 v33, 0xffff0000, v50
	v_lshlrev_b32_e32 v50, 16, v51
	v_and_b32_e32 v51, 0xffff0000, v51
	v_mul_f32_e32 v18, v51, v51
	v_and_b32_e32 v31, 0xffff0000, v47
	v_and_b32_e32 v30, 0xffff0000, v46
	v_and_b32_e32 v21, 0xffff0000, v48
	v_mul_f32_e32 v20, v33, v33
	v_pk_fma_f32 v[52:53], v[50:51], v[50:51], v[18:19] op_sel_hi:[1,1,0]
	v_lshlrev_b32_e32 v29, 16, v47
	v_lshlrev_b32_e32 v28, 16, v46
	v_pk_mul_f32 v[18:19], v[30:31], v[30:31]
	v_lshlrev_b32_e32 v24, 16, v44
	v_and_b32_e32 v25, 0xffff0000, v44
	v_lshlrev_b32_e32 v26, 16, v45
	v_and_b32_e32 v27, 0xffff0000, v45
	v_lshlrev_b32_e32 v23, 16, v48
	v_pk_fma_f32 v[44:45], v[32:33], v[32:33], v[20:21] op_sel_hi:[1,1,0]
	v_pk_fma_f32 v[46:47], v[28:29], v[28:29], v[18:19]
	v_lshlrev_b32_e32 v18, 16, v49
	v_and_b32_e32 v19, 0xffff0000, v49
	v_mov_b32_e32 v22, v44
	v_mov_b32_e32 v48, v52
	v_mov_b32_e32 v49, v23
	v_mul_f32_e32 v54, v21, v21
	v_pk_add_f32 v[44:45], v[44:45], v[52:53]
	v_pk_mul_f32 v[48:49], v[22:23], v[48:49]
	v_pk_add_f32 v[46:47], v[46:47], v[46:47] op_sel:[0,1] op_sel_hi:[1,0]
	v_mov_b32_e32 v45, v49
	v_mov_b32_e32 v47, v54
	v_mul_f32_e32 v20, v25, v25
	v_pk_add_f32 v[44:45], v[44:45], v[46:47]
	v_pk_fma_f32 v[46:47], v[24:25], v[24:25], v[20:21] op_sel_hi:[1,1,0]
	v_mul_f32_e32 v20, v27, v27
	v_mul_f32_e32 v55, v18, v18
	v_mul_f32_e32 v56, v19, v19
	v_pk_fma_f32 v[48:49], v[26:27], v[26:27], v[20:21] op_sel_hi:[1,1,0]
	v_mov_b32_e32 v47, v55
	v_mov_b32_e32 v49, v56
	v_pk_add_f32 v[46:47], v[46:47], v[48:49]
	s_nop 0
	v_pk_add_f32 v[44:45], v[44:45], v[46:47]
	s_nop 0
	v_add_f32_e32 v20, v44, v45
	v_mov_b64_e32 v[44:45], v[140:141]
	v_mov_b64_e32 v[46:47], v[142:143]
	ds_bpermute_b32 v22, v72, v20
	s_waitcnt lgkmcnt(0)
	v_add_f32_e32 v20, v20, v22
	ds_bpermute_b32 v22, v73, v20
	s_waitcnt lgkmcnt(0)
	v_add_f32_e32 v20, v20, v22
	ds_bpermute_b32 v22, v74, v20
	s_waitcnt lgkmcnt(0)
	v_add_f32_e32 v20, v20, v22
	ds_bpermute_b32 v22, v75, v20
	s_waitcnt lgkmcnt(0)
; __device__ __forceinline__ float bflo(unsigned w) { return __uint_as_float(w << 16); }
; __device__ __forceinline__ float bfhi(unsigned w) { return __uint_as_float(w & 0xffff0000u); }
; __device__ __forceinline__ unsigned pk2(float lo, float hi) { f32x2_t v = {lo, hi}; bf16x2_t b = __builtin_convertvector(v, bf16x2_t); return __builtin_bit_cast(unsigned, b); }
; __device__ __forceinline__ float bflo(unsigned w) { return __uint_as_float(w << 16); }
; __device__ __forceinline__ float bfhi(unsigned w) { return __uint_as_float(w & 0xffff0000u); }
; __device__ __forceinline__ void phase_rowwise(const bf16_t* ysrc, const float* hin, float* hout, float wt, const float* g_post, const float* g_pre, bf16_t* xn) {
;     ...
;             if (ysrc) {
;                 f32x4 y[4]; float s = 0.f;
; #pragma unroll
;                 for (int j = 0; j < 4; ++j) { const v2u w = half ? yb[j] : ya[j]; y[j] = (f32x4){bflo(w.x), bfhi(w.x), bflo(w.y), bfhi(w.y)}; s += (y[j].x * y[j].x + y[j].y * y[j].y) + (y[j].z * y[j].z + y[j].w * y[j].w); }
;                 const float rinv = wt * rsqrtf(wave_sum(s) * (1.f / DM) + NORM_EPS);
; #pragma unroll
;                 for (int j = 0; j < 4; ++j) { const f32x4 g = *((const f32x4*)g_post + lane + 64 * j); h[j] = h[j] + y[j] * g * rinv; }
;             }
;             f32x4* ho = (f32x4*)(hout + (size_t)r * DM) + lane;
; #pragma unroll
;             for (int j = 0; j < 4; ++j) ho[64 * j] = h[j];
;             if (g_pre) {
;                 float s = 0.f;
; #pragma unroll
;                 for (int j = 0; j < 4; ++j) s += (h[j].x * h[j].x + h[j].y * h[j].y) + (h[j].z * h[j].z + h[j].w * h[j].w);
;                 const float rinv = rsqrtf(wave_sum(s) * (1.f / DM) + NORM_EPS);
;                 unsigned long long* o8 = (unsigned long long*)(xn + (size_t)r * DM) + lane;
; #pragma unroll
;                 for (int j = 0; j < 4; ++j) { const f32x4 g = *((const f32x4*)g_pre + lane + 64 * j); const f32x4 v = h[j] * g * rinv;
;                     o8[64 * j] = (unsigned long long)pk2(v.x, v.y) | ((unsigned long long)pk2(v.z, v.w) << 32); }
	v_add_f32_e32 v20, v20, v22
	ds_bpermute_b32 v22, v76, v20
	s_waitcnt lgkmcnt(0)
	v_add_f32_e32 v20, v20, v22
	ds_bpermute_b32 v22, v77, v20
	s_waitcnt lgkmcnt(0)
	v_add_f32_e32 v20, v20, v22
	v_fmamk_f32 v20, v20, 0x3a800000, v184
	v_cmp_gt_f32_e32 vcc, s61, v20
	v_mul_f32_e32 v22, 0x4b800000, v20
	v_pk_mul_f32 v[32:33], v[44:45], v[32:33]
	v_cndmask_b32_e32 v20, v20, v22, vcc
	v_rsq_f32_e32 v20, v20
	v_pk_mul_f32 v[44:45], v[46:47], v[50:51]
	v_mul_f32_e32 v22, 0x45800000, v20
	v_cndmask_b32_e32 v20, v20, v22, vcc
	v_mul_f32_e32 v22, 0.5, v20
	v_pk_fma_f32 v[16:17], v[44:45], v[22:23], v[16:17] op_sel_hi:[1,0,1]
	v_mov_b64_e32 v[44:45], v[144:145]
	v_mov_b64_e32 v[46:47], v[146:147]
	v_pk_fma_f32 v[14:15], v[32:33], v[22:23], v[14:15] op_sel_hi:[1,0,1]
	v_mov_b32_e32 v33, v30
	v_mov_b32_e32 v30, v29
	v_mov_b32_e32 v32, v28
	v_mov_b32_e32 v20, v23
	s_and_b64 vcc, exec, s[4:5]
	v_pk_mul_f32 v[28:29], v[46:47], v[30:31]
	s_nop 0
	v_pk_fma_f32 v[12:13], v[28:29], v[22:23], v[12:13] op_sel_hi:[1,0,1]
	v_mov_b64_e32 v[28:29], v[148:149]
	v_mov_b64_e32 v[30:31], v[150:151]
	v_pk_mul_f32 v[32:33], v[44:45], v[32:33]
	v_pk_mul_f32 v[24:25], v[28:29], v[24:25]
	v_pk_mul_f32 v[26:27], v[30:31], v[26:27]
	v_pk_fma_f32 v[6:7], v[24:25], v[22:23], v[6:7] op_sel_hi:[1,0,1]
	v_pk_fma_f32 v[8:9], v[26:27], v[22:23], v[8:9] op_sel_hi:[1,0,1]
	v_mov_b64_e32 v[24:25], v[152:153]
	v_mov_b64_e32 v[26:27], v[154:155]
	v_pk_fma_f32 v[10:11], v[32:33], v[22:23], v[10:11] op_sel_hi:[1,0,1]
	v_pk_mul_f32 v[20:21], v[20:21], v[24:25]
	v_pk_mul_f32 v[18:19], v[18:19], v[26:27]
	v_pk_fma_f32 v[2:3], v[20:21], v[22:23], v[2:3] op_sel_hi:[1,0,1]
	v_pk_fma_f32 v[4:5], v[18:19], v[22:23], v[4:5] op_sel_hi:[1,0,1]
	v_lshl_add_u64 v[18:19], s[12:13], 0, v[0:1]
	global_store_dwordx4 v[18:19], v[14:17], off
	global_store_dwordx4 v[18:19], v[10:13], off offset:1024
	global_store_dwordx4 v[18:19], v[6:9], off offset:2048
	global_store_dwordx4 v[18:19], v[2:5], off offset:3072
	s_cbranch_vccnz .LBB0_265
	v_pk_mul_f32 v[18:19], v[16:17], v[16:17]
	v_pk_mul_f32 v[20:21], v[14:15], v[14:15]
	s_mov_b32 s4, 0x16e00000
	v_pk_mov_b32 v[22:23], v[20:21], v[18:19] op_sel:[1,0]
	v_mov_b32_e32 v21, v19
	v_pk_add_f32 v[18:19], v[22:23], v[20:21]
	v_pk_mul_f32 v[20:21], v[12:13], v[12:13]
	v_pk_add_f32 v[18:19], v[18:19], v[18:19] op_sel_hi:[0,1]
	v_pk_mul_f32 v[22:23], v[10:11], v[10:11]
	v_mul_f32_e32 v18, v6, v6
	v_pk_mov_b32 v[24:25], v[22:23], v[20:21] op_sel:[1,0]
	v_mov_b32_e32 v23, v21
	v_pk_add_f32 v[20:21], v[24:25], v[22:23]
	v_pk_fma_f32 v[22:23], v[6:7], v[6:7], v[18:19] op_sel_hi:[1,1,0]
	v_mul_f32_e32 v18, v8, v8
	v_pk_add_f32 v[20:21], v[20:21], v[20:21] op_sel_hi:[0,1]
	v_pk_fma_f32 v[24:25], v[8:9], v[8:9], v[18:19] op_sel_hi:[1,1,0]
	v_mul_f32_e32 v22, v2, v2
	v_mul_f32_e32 v24, v3, v3
	v_mul_f32_e32 v18, v4, v4
	v_mul_f32_e32 v20, v5, v5
	v_pk_add_f32 v[22:23], v[22:23], v[24:25]
	v_pk_add_f32 v[18:19], v[18:19], v[20:21]
	v_lshl_add_u64 v[20:21], s[8:9], 0, v[36:37]
	v_pk_add_f32 v[18:19], v[22:23], v[18:19]
	v_mov_b64_e32 v[22:23], v[156:157]
	v_mov_b64_e32 v[24:25], v[158:159]
	v_add_f32_e32 v18, v18, v19
	ds_bpermute_b32 v19, v72, v18
	s_waitcnt lgkmcnt(0)
	v_add_f32_e32 v18, v18, v19
	ds_bpermute_b32 v19, v73, v18
	s_waitcnt lgkmcnt(0)
	v_add_f32_e32 v18, v18, v19
	ds_bpermute_b32 v19, v74, v18
	s_waitcnt lgkmcnt(0)
	v_add_f32_e32 v18, v18, v19
	ds_bpermute_b32 v19, v75, v18
	s_waitcnt lgkmcnt(0)
	v_add_f32_e32 v18, v18, v19
	ds_bpermute_b32 v19, v76, v18
	s_waitcnt lgkmcnt(0)
	v_add_f32_e32 v18, v18, v19
	ds_bpermute_b32 v19, v77, v18
	s_waitcnt lgkmcnt(0)
	v_add_f32_e32 v18, v18, v19
	v_fmamk_f32 v18, v18, 0x3a800000, v184
	v_cmp_gt_f32_e32 vcc, s61, v18
	v_mul_f32_e32 v19, 0x4b800000, v18
	v_pk_mul_f32 v[16:17], v[16:17], v[24:25]
	v_cndmask_b32_e32 v18, v18, v19, vcc
	v_rsq_f32_e32 v18, v18
	v_pk_mul_f32 v[14:15], v[14:15], v[22:23]
	v_mul_f32_e32 v19, 0x45800000, v18
	v_cndmask_b32_e32 v18, v18, v19, vcc
	v_pk_mul_f32 v[16:17], v[16:17], v[18:19] op_sel_hi:[1,0]
	v_pk_mul_f32 v[14:15], v[14:15], v[18:19] op_sel_hi:[1,0]
	v_add_co_u32_e32 v20, vcc, s4, v20
	v_cvt_pk_bf16_f32 v14, v14, v15
	v_cvt_pk_bf16_f32 v15, v16, v17
	v_addc_co_u32_e32 v21, vcc, 0, v21, vcc
	global_store_dwordx2 v[20:21], v[14:15], off
	v_mov_b64_e32 v[14:15], v[160:161]
	v_mov_b64_e32 v[16:17], v[162:163]
	v_pk_mul_f32 v[12:13], v[12:13], v[16:17]
	v_pk_mul_f32 v[10:11], v[10:11], v[14:15]
	v_pk_mul_f32 v[12:13], v[12:13], v[18:19] op_sel_hi:[1,0]
	v_pk_mul_f32 v[10:11], v[10:11], v[18:19] op_sel_hi:[1,0]
	s_nop 0
	v_cvt_pk_bf16_f32 v10, v10, v11
	v_cvt_pk_bf16_f32 v11, v12, v13
	global_store_dwordx2 v[20:21], v[10:11], off offset:512
	v_mov_b64_e32 v[10:11], v[164:165]
	v_mov_b64_e32 v[12:13], v[166:167]
	v_pk_mul_f32 v[8:9], v[8:9], v[12:13]
	v_pk_mul_f32 v[6:7], v[6:7], v[10:11]
	v_pk_mul_f32 v[8:9], v[8:9], v[18:19] op_sel_hi:[1,0]
	v_pk_mul_f32 v[6:7], v[6:7], v[18:19] op_sel_hi:[1,0]
	s_nop 0
	v_cvt_pk_bf16_f32 v6, v6, v7
	v_cvt_pk_bf16_f32 v7, v8, v9
	global_store_dwordx2 v[20:21], v[6:7], off offset:1024
	v_mov_b64_e32 v[6:7], v[168:169]
	v_mov_b64_e32 v[8:9], v[170:171]
	v_pk_mul_f32 v[4:5], v[4:5], v[8:9]
	v_pk_mul_f32 v[2:3], v[2:3], v[6:7]
	v_pk_mul_f32 v[4:5], v[4:5], v[18:19] op_sel_hi:[1,0]
	v_pk_mul_f32 v[2:3], v[2:3], v[18:19] op_sel_hi:[1,0]
	s_nop 0
	v_cvt_pk_bf16_f32 v2, v2, v3
	v_cvt_pk_bf16_f32 v3, v4, v5
	global_store_dwordx2 v[20:21], v[2:3], off offset:1536
	s_branch .LBB0_265

; __device__ __forceinline__ float bflo(unsigned w) { return __uint_as_float(w << 16); }
; __device__ __forceinline__ float bfhi(unsigned w) { return __uint_as_float(w & 0xffff0000u); }
; __device__ __forceinline__ unsigned pk2(float lo, float hi) { f32x2_t v = {lo, hi}; bf16x2_t b = __builtin_convertvector(v, bf16x2_t); return __builtin_bit_cast(unsigned, b); }
; __device__ __forceinline__ float bflo(unsigned w) { return __uint_as_float(w << 16); }
; __device__ __forceinline__ float bfhi(unsigned w) { return __uint_as_float(w & 0xffff0000u); }
; __device__ __forceinline__ void phase_prep(const Params& P, int l) {
;     ...
;     for (int t = gw; t < T; t += ngw) {
;         const unsigned* cur = (const unsigned*)(P1 + (size_t)t * NP1);
;         const unsigned* prv = (const unsigned*)(P1 + (size_t)(t > 0 ? t - 1 : 0) * NP1);
;         const bool hasp = t > 0;
; #pragma unroll
;         for (int i = 0; i < 14; ++i) {
;             const int j = lane + 64 * i, col = 2 * j;
;             const unsigned cw = cur[j], pw = hasp ? prv[j] : 0u;
;             const float c0 = bflo(cw), c1 = bfhi(cw), p0 = bflo(pw), p1 = bfhi(pw);
;             float m0 = c0 + (p0 - c0) * mu[col], m1 = c1 + (p1 - c1) * mu[col + 1];
;             if (i < 4) { *(unsigned*)(RB + (size_t)t * 512 + col) = pk2(m0, m1); }
;             else if (i < 8) { *(unsigned*)(KB + (size_t)t * 512 + col - 512) = pk2(m0, m1); }
;             else if (i < 12) { const unsigned w = pk2(m0, m1); *(unsigned*)(VB + (size_t)t * 512 + col - 1024) = w; if (l == 0) *(unsigned*)(VF + (size_t)t * 512 + col - 1024) = w; }
.LBB0_499:
	v_lshl_add_u64 v[58:59], s[16:17], 0, v[56:57]
	v_add_co_u32_e32 v60, vcc, 0x3e00000, v58
	s_cmp_gt_i32 s14, 0
	s_nop 0
	v_addc_co_u32_e32 v61, vcc, 0, v59, vcc
	s_cselect_b64 s[12:13], -1, 0
	s_max_i32 s10, s14, 1
	s_add_i32 s10, s10, -1
	s_mul_hi_u32 s11, s10, 0x1400
	s_mulk_i32 s10, 0x1400
	s_add_u32 s52, s54, s10
	s_addc_u32 s53, s55, s11
	v_lshlrev_b32_e32 v135, 2, v2
	v_add_co_u32_e32 v136, vcc, 0x3e01000, v58
	global_load_dword v100, v[60:61], off
	global_load_dword v115, v135, s[52:53]
	global_load_dword v101, v[60:61], off offset:256
	v_addc_co_u32_e32 v137, vcc, 0, v59, vcc
	global_load_dword v116, v135, s[52:53] offset:256
	global_load_dword v102, v[60:61], off offset:512
	global_load_dword v117, v135, s[52:53] offset:512
	global_load_dword v103, v[60:61], off offset:768
	global_load_dword v118, v135, s[52:53] offset:768
	global_load_dword v104, v[60:61], off offset:1024
	global_load_dword v119, v135, s[52:53] offset:1024
	global_load_dword v105, v[60:61], off offset:1280
	global_load_dword v120, v135, s[52:53] offset:1280
	global_load_dword v106, v[60:61], off offset:1536
	global_load_dword v121, v135, s[52:53] offset:1536
	global_load_dword v107, v[60:61], off offset:1792
	global_load_dword v122, v135, s[52:53] offset:1792
	global_load_dword v108, v[60:61], off offset:2048
	global_load_dword v123, v135, s[52:53] offset:2048
	global_load_dword v109, v[60:61], off offset:2304
	global_load_dword v124, v135, s[52:53] offset:2304
	global_load_dword v110, v[60:61], off offset:2560
	global_load_dword v125, v135, s[52:53] offset:2560
	global_load_dword v111, v[60:61], off offset:2816
	global_load_dword v126, v135, s[52:53] offset:2816
	global_load_dword v112, v[60:61], off offset:3072
	global_load_dword v127, v135, s[52:53] offset:3072
	global_load_dword v113, v[60:61], off offset:3328
	global_load_dword v128, v135, s[52:53] offset:3328
	global_load_dword v114, v[60:61], off offset:3584
	global_load_dword v129, v135, s[52:53] offset:3584
	global_load_dword v130, v[60:61], off offset:3648
	global_load_dword v131, v[60:61], off offset:3904
	global_load_dword v132, v[136:137], off offset:64
	global_load_dword v133, v[136:137], off offset:320
	global_load_dword v134, v[136:137], off offset:576
	s_waitcnt vmcnt(33)
	v_mov_b32_e32 v0, v100
	v_cndmask_b32_e64 v45, 0, v115, s[12:13]
	v_and_b32_e32 v61, 0xffff0000, v45
	v_and_b32_e32 v63, 0xffff0000, v0
	v_lshlrev_b32_e32 v60, 16, v45
	v_lshlrev_b32_e32 v62, 16, v0
	v_pk_add_f32 v[60:61], v[60:61], v[62:63] neg_lo:[0,1] neg_hi:[0,1]
	s_nop 0
	v_pk_fma_f32 v[60:61], v[30:31], v[60:61], v[62:63]
	s_nop 0
	v_cvt_pk_bf16_f32 v0, v60, v61
	v_lshl_add_u64 v[60:61], s[16:17], 0, v[50:51]
	v_add_co_u32_e32 v62, vcc, 0x12e00000, v60
	s_nop 1
	v_addc_co_u32_e32 v63, vcc, 0, v61, vcc
	global_store_dword v[62:63], v0, off
	v_add_co_u32_e32 v62, vcc, 0x3e00000, v58
	v_mov_b32_e32 v0, 0
	s_nop 0
	v_addc_co_u32_e32 v63, vcc, 0, v59, vcc
	s_waitcnt vmcnt(32)
	v_mov_b32_e32 v45, v101
	v_cndmask_b32_e64 v62, 0, 1, s[12:13]
	v_cmp_ne_u32_e64 s[10:11], 1, v62
	s_andn2_b64 vcc, exec, s[12:13]
	v_mov_b32_e32 v62, 0
	s_cbranch_vccnz .LBB0_504
	v_mov_b32_e32 v62, v116
.LBB0_504:
	v_and_b32_e32 v63, 0xffff0000, v62
	v_and_b32_e32 v65, 0xffff0000, v45
	v_lshlrev_b32_e32 v62, 16, v62
	v_lshlrev_b32_e32 v64, 16, v45
	v_pk_add_f32 v[62:63], v[62:63], v[64:65] neg_lo:[0,1] neg_hi:[0,1]
	s_nop 0
	v_pk_fma_f32 v[62:63], v[4:5], v[62:63], v[64:65]
	s_nop 0
	v_cvt_pk_bf16_f32 v45, v62, v63
	v_add_co_u32_e32 v62, vcc, 0x12e00000, v60
	s_nop 1
	v_addc_co_u32_e32 v63, vcc, 0, v61, vcc
	global_store_dword v[62:63], v45, off offset:256
	v_add_co_u32_e32 v62, vcc, 0x3e00000, v58
	s_nop 1
	v_addc_co_u32_e32 v63, vcc, 0, v59, vcc
	s_waitcnt vmcnt(31)
	v_mov_b32_e32 v45, v102
	s_and_b64 vcc, exec, s[10:11]
	s_cbranch_vccnz .LBB0_506
	v_mov_b32_e32 v0, v117
.LBB0_506:
	v_and_b32_e32 v63, 0xffff0000, v0
	v_and_b32_e32 v65, 0xffff0000, v45
	v_lshlrev_b32_e32 v62, 16, v0
	v_lshlrev_b32_e32 v64, 16, v45
	v_pk_add_f32 v[62:63], v[62:63], v[64:65] neg_lo:[0,1] neg_hi:[0,1]
	s_nop 0
	v_pk_fma_f32 v[62:63], v[6:7], v[62:63], v[64:65]
	s_nop 0
	v_cvt_pk_bf16_f32 v0, v62, v63
	v_add_co_u32_e32 v62, vcc, 0x12e00000, v60
	s_nop 1
	v_addc_co_u32_e32 v63, vcc, 0, v61, vcc
	global_store_dword v[62:63], v0, off offset:512
	v_add_co_u32_e32 v62, vcc, 0x3e00000, v58
	v_mov_b32_e32 v0, 0
	s_nop 0
	v_addc_co_u32_e32 v63, vcc, 0, v59, vcc
	s_waitcnt vmcnt(30)
	v_mov_b32_e32 v45, v103
	s_and_b64 vcc, exec, s[10:11]
	v_mov_b32_e32 v62, 0
	s_cbranch_vccnz .LBB0_508
	v_mov_b32_e32 v62, v118
; __device__ __forceinline__ float bflo(unsigned w) { return __uint_as_float(w << 16); }
; __device__ __forceinline__ float bfhi(unsigned w) { return __uint_as_float(w & 0xffff0000u); }
; __device__ __forceinline__ unsigned pk2(float lo, float hi) { f32x2_t v = {lo, hi}; bf16x2_t b = __builtin_convertvector(v, bf16x2_t); return __builtin_bit_cast(unsigned, b); }
; __device__ __forceinline__ float bflo(unsigned w) { return __uint_as_float(w << 16); }
; __device__ __forceinline__ float bfhi(unsigned w) { return __uint_as_float(w & 0xffff0000u); }
; __device__ __forceinline__ void phase_prep(const Params& P, int l) {
;     ...
;         for (int i = 0; i < 14; ++i) {
;             const int j = lane + 64 * i, col = 2 * j;
;             const unsigned cw = cur[j], pw = hasp ? prv[j] : 0u;
;             const float c0 = bflo(cw), c1 = bfhi(cw), p0 = bflo(pw), p1 = bfhi(pw);
;             float m0 = c0 + (p0 - c0) * mu[col], m1 = c1 + (p1 - c1) * mu[col + 1];
;             if (i < 4) { *(unsigned*)(RB + (size_t)t * 512 + col) = pk2(m0, m1); }
;             else if (i < 8) { *(unsigned*)(KB + (size_t)t * 512 + col - 512) = pk2(m0, m1); }
;             else if (i < 12) { const unsigned w = pk2(m0, m1); *(unsigned*)(VB + (size_t)t * 512 + col - 1024) = w; if (l == 0) *(unsigned*)(VF + (size_t)t * 512 + col - 1024) = w; }
.LBB0_508:
	v_and_b32_e32 v63, 0xffff0000, v62
	v_and_b32_e32 v65, 0xffff0000, v45
	v_lshlrev_b32_e32 v62, 16, v62
	v_lshlrev_b32_e32 v64, 16, v45
	v_pk_add_f32 v[62:63], v[62:63], v[64:65] neg_lo:[0,1] neg_hi:[0,1]
	s_nop 0
	v_pk_fma_f32 v[62:63], v[8:9], v[62:63], v[64:65]
	s_nop 0
	v_cvt_pk_bf16_f32 v45, v62, v63
	v_add_co_u32_e32 v62, vcc, 0x12e00000, v60
	s_nop 1
	v_addc_co_u32_e32 v63, vcc, 0, v61, vcc
	global_store_dword v[62:63], v45, off offset:768
	v_add_co_u32_e32 v62, vcc, 0x3e00000, v58
	s_nop 1
	v_addc_co_u32_e32 v63, vcc, 0, v59, vcc
	s_waitcnt vmcnt(29)
	v_mov_b32_e32 v45, v104
	s_and_b64 vcc, exec, s[10:11]
	s_cbranch_vccnz .LBB0_510
	v_mov_b32_e32 v0, v119
.LBB0_510:
	v_lshlrev_b32_e32 v62, 16, v45
	v_and_b32_e32 v63, 0xffff0000, v45
	v_lshlrev_b32_e32 v64, 16, v0
	v_and_b32_e32 v65, 0xffff0000, v0
	v_pk_add_f32 v[64:65], v[64:65], v[62:63] neg_lo:[0,1] neg_hi:[0,1]
	s_nop 0
	v_pk_fma_f32 v[62:63], v[10:11], v[64:65], v[62:63]
	s_nop 0
	v_cvt_pk_bf16_f32 v0, v62, v63
	v_add_co_u32_e32 v62, vcc, 0x13e00000, v60
	s_nop 1
	v_addc_co_u32_e32 v63, vcc, 0, v61, vcc
	global_store_dword v[62:63], v0, off
	v_add_co_u32_e32 v62, vcc, 0x3e00000, v58
	v_mov_b32_e32 v0, 0
	s_nop 0
	v_addc_co_u32_e32 v63, vcc, 0, v59, vcc
	s_waitcnt vmcnt(28)
	v_mov_b32_e32 v45, v105
	s_and_b64 vcc, exec, s[10:11]
	v_mov_b32_e32 v62, 0
	s_cbranch_vccnz .LBB0_512
	v_mov_b32_e32 v62, v120
.LBB0_512:
	v_lshlrev_b32_e32 v64, 16, v45
	v_and_b32_e32 v65, 0xffff0000, v45
	v_lshlrev_b32_e32 v66, 16, v62
	v_and_b32_e32 v67, 0xffff0000, v62
	v_pk_add_f32 v[62:63], v[66:67], v[64:65] neg_lo:[0,1] neg_hi:[0,1]
	s_nop 0
	v_pk_fma_f32 v[62:63], v[12:13], v[62:63], v[64:65]
	s_nop 0
	v_cvt_pk_bf16_f32 v45, v62, v63
	v_add_co_u32_e32 v62, vcc, 0x13e00000, v60
	s_nop 1
	v_addc_co_u32_e32 v63, vcc, 0, v61, vcc
	global_store_dword v[62:63], v45, off offset:256
	v_add_co_u32_e32 v62, vcc, 0x3e00000, v58
	s_nop 1
	v_addc_co_u32_e32 v63, vcc, 0, v59, vcc
	s_waitcnt vmcnt(27)
	v_mov_b32_e32 v45, v106
	s_and_b64 vcc, exec, s[10:11]
	s_cbranch_vccnz .LBB0_514
	v_mov_b32_e32 v0, v121
.LBB0_514:
	v_lshlrev_b32_e32 v62, 16, v45
	v_and_b32_e32 v63, 0xffff0000, v45
	v_lshlrev_b32_e32 v64, 16, v0
	v_and_b32_e32 v65, 0xffff0000, v0
	v_pk_add_f32 v[64:65], v[64:65], v[62:63] neg_lo:[0,1] neg_hi:[0,1]
	s_nop 0
	v_pk_fma_f32 v[62:63], v[14:15], v[64:65], v[62:63]
	s_nop 0
	v_cvt_pk_bf16_f32 v0, v62, v63
	v_add_co_u32_e32 v62, vcc, 0x13e00000, v60
	s_nop 1
	v_addc_co_u32_e32 v63, vcc, 0, v61, vcc
	global_store_dword v[62:63], v0, off offset:512
	v_add_co_u32_e32 v62, vcc, 0x3e00000, v58
	v_mov_b32_e32 v0, 0
	s_nop 0
	v_addc_co_u32_e32 v63, vcc, 0, v59, vcc
	s_waitcnt vmcnt(26)
	v_mov_b32_e32 v45, v107
	s_and_b64 vcc, exec, s[10:11]
	v_mov_b32_e32 v62, 0
	s_cbranch_vccnz .LBB0_516
	v_mov_b32_e32 v62, v122
.LBB0_516:
	v_lshlrev_b32_e32 v64, 16, v45
	v_and_b32_e32 v65, 0xffff0000, v45
	v_lshlrev_b32_e32 v66, 16, v62
	v_and_b32_e32 v67, 0xffff0000, v62
	v_pk_add_f32 v[62:63], v[66:67], v[64:65] neg_lo:[0,1] neg_hi:[0,1]
	s_nop 0
	v_pk_fma_f32 v[62:63], v[16:17], v[62:63], v[64:65]
	s_nop 0
	v_cvt_pk_bf16_f32 v45, v62, v63
	v_add_co_u32_e32 v62, vcc, 0x13e00000, v60
	s_nop 1
	v_addc_co_u32_e32 v63, vcc, 0, v61, vcc
	global_store_dword v[62:63], v45, off offset:768
	v_add_co_u32_e32 v62, vcc, 0x3e00000, v58
	s_nop 1
	v_addc_co_u32_e32 v63, vcc, 0, v59, vcc
	s_waitcnt vmcnt(25)
	v_mov_b32_e32 v45, v108
	s_and_b64 vcc, exec, s[10:11]
	s_cbranch_vccnz .LBB0_518
	v_mov_b32_e32 v0, v123
.LBB0_518:
	v_lshlrev_b32_e32 v62, 16, v45
	v_and_b32_e32 v63, 0xffff0000, v45
	v_lshlrev_b32_e32 v64, 16, v0
	v_and_b32_e32 v65, 0xffff0000, v0
	v_pk_add_f32 v[64:65], v[64:65], v[62:63] neg_lo:[0,1] neg_hi:[0,1]
	v_cndmask_b32_e64 v45, 0, 1, s[36:37]
	v_pk_fma_f32 v[62:63], v[18:19], v[64:65], v[62:63]
	v_cmp_ne_u32_e64 s[12:13], 1, v45
	v_cvt_pk_bf16_f32 v0, v62, v63
	v_add_co_u32_e32 v62, vcc, 0x14e00000, v60
	s_nop 1
	v_addc_co_u32_e32 v63, vcc, 0, v61, vcc
	s_andn2_b64 vcc, exec, s[36:37]
	global_store_dword v[62:63], v0, off
	s_cbranch_vccnz .LBB0_520
	v_add_co_u32_e32 v62, vcc, 0x2e00000, v60
	s_nop 1
	v_addc_co_u32_e32 v63, vcc, 0, v61, vcc
	global_store_dword v[62:63], v0, off
.LBB0_520:
	v_add_co_u32_e32 v62, vcc, 0x3e00000, v58
	s_nop 1
	v_addc_co_u32_e32 v63, vcc, 0, v59, vcc
	s_waitcnt vmcnt(24)
	v_mov_b32_e32 v0, v109
	s_and_b64 vcc, exec, s[10:11]
	s_cbranch_vccnz .LBB0_522
	v_mov_b32_e32 v45, v124
	s_branch .LBB0_523

; __device__ __forceinline__ float bflo(unsigned w) { return __uint_as_float(w << 16); }
; __device__ __forceinline__ float bfhi(unsigned w) { return __uint_as_float(w & 0xffff0000u); }
; __device__ __forceinline__ unsigned pk2(float lo, float hi) { f32x2_t v = {lo, hi}; bf16x2_t b = __builtin_convertvector(v, bf16x2_t); return __builtin_bit_cast(unsigned, b); }
; __device__ __forceinline__ float bflo(unsigned w) { return __uint_as_float(w << 16); }
; __device__ __forceinline__ float bfhi(unsigned w) { return __uint_as_float(w & 0xffff0000u); }
; __device__ __forceinline__ void phase_prep(const Params& P, int l) {
;     ...
;         for (int i = 0; i < 14; ++i) {
;             const int j = lane + 64 * i, col = 2 * j;
;             const unsigned cw = cur[j], pw = hasp ? prv[j] : 0u;
;             const float c0 = bflo(cw), c1 = bfhi(cw), p0 = bflo(pw), p1 = bfhi(pw);
;             float m0 = c0 + (p0 - c0) * mu[col], m1 = c1 + (p1 - c1) * mu[col + 1];
;             if (i < 4) { *(unsigned*)(RB + (size_t)t * 512 + col) = pk2(m0, m1); }
;             else if (i < 8) { *(unsigned*)(KB + (size_t)t * 512 + col - 512) = pk2(m0, m1); }
;             else if (i < 12) { const unsigned w = pk2(m0, m1); *(unsigned*)(VB + (size_t)t * 512 + col - 1024) = w; if (l == 0) *(unsigned*)(VF + (size_t)t * 512 + col - 1024) = w; }
.LBB0_523:
	v_lshlrev_b32_e32 v62, 16, v0
	v_and_b32_e32 v63, 0xffff0000, v0
	v_lshlrev_b32_e32 v64, 16, v45
	v_and_b32_e32 v65, 0xffff0000, v45
	v_pk_add_f32 v[64:65], v[64:65], v[62:63] neg_lo:[0,1] neg_hi:[0,1]
	s_nop 0
	v_pk_fma_f32 v[62:63], v[20:21], v[64:65], v[62:63]
	s_nop 0
	v_cvt_pk_bf16_f32 v0, v62, v63
	v_add_co_u32_e32 v62, vcc, 0x14e00000, v60
	s_nop 1
	v_addc_co_u32_e32 v63, vcc, 0, v61, vcc
	s_and_b64 vcc, exec, s[12:13]
	global_store_dword v[62:63], v0, off offset:256
	s_cbranch_vccnz .LBB0_525
	v_add_co_u32_e32 v62, vcc, 0x2e00000, v60
	s_nop 1
	v_addc_co_u32_e32 v63, vcc, 0, v61, vcc
	global_store_dword v[62:63], v0, off offset:256
.LBB0_525:
	v_add_co_u32_e32 v62, vcc, 0x3e00000, v58
	s_nop 1
	v_addc_co_u32_e32 v63, vcc, 0, v59, vcc
	s_waitcnt vmcnt(23)
	v_mov_b32_e32 v0, v110
	s_and_b64 vcc, exec, s[10:11]
	s_cbranch_vccnz .LBB0_527
	v_mov_b32_e32 v45, v125
	s_branch .LBB0_528

; __device__ __forceinline__ float bflo(unsigned w) { return __uint_as_float(w << 16); }
; __device__ __forceinline__ float bfhi(unsigned w) { return __uint_as_float(w & 0xffff0000u); }
; __device__ __forceinline__ unsigned pk2(float lo, float hi) { f32x2_t v = {lo, hi}; bf16x2_t b = __builtin_convertvector(v, bf16x2_t); return __builtin_bit_cast(unsigned, b); }
; __device__ __forceinline__ float bflo(unsigned w) { return __uint_as_float(w << 16); }
; __device__ __forceinline__ float bfhi(unsigned w) { return __uint_as_float(w & 0xffff0000u); }
; __device__ __forceinline__ void phase_prep(const Params& P, int l) {
;     ...
;         for (int i = 0; i < 14; ++i) {
;             const int j = lane + 64 * i, col = 2 * j;
;             const unsigned cw = cur[j], pw = hasp ? prv[j] : 0u;
;             const float c0 = bflo(cw), c1 = bfhi(cw), p0 = bflo(pw), p1 = bfhi(pw);
;             float m0 = c0 + (p0 - c0) * mu[col], m1 = c1 + (p1 - c1) * mu[col + 1];
;             if (i < 4) { *(unsigned*)(RB + (size_t)t * 512 + col) = pk2(m0, m1); }
;             else if (i < 8) { *(unsigned*)(KB + (size_t)t * 512 + col - 512) = pk2(m0, m1); }
;             else if (i < 12) { const unsigned w = pk2(m0, m1); *(unsigned*)(VB + (size_t)t * 512 + col - 1024) = w; if (l == 0) *(unsigned*)(VF + (size_t)t * 512 + col - 1024) = w; }
.LBB0_528:
	v_lshlrev_b32_e32 v62, 16, v0
	v_and_b32_e32 v63, 0xffff0000, v0
	v_lshlrev_b32_e32 v64, 16, v45
	v_and_b32_e32 v65, 0xffff0000, v45
	v_pk_add_f32 v[64:65], v[64:65], v[62:63] neg_lo:[0,1] neg_hi:[0,1]
	s_nop 0
	v_pk_fma_f32 v[62:63], v[22:23], v[64:65], v[62:63]
	s_nop 0
	v_cvt_pk_bf16_f32 v0, v62, v63
	v_add_co_u32_e32 v62, vcc, 0x14e00000, v60
	s_nop 1
	v_addc_co_u32_e32 v63, vcc, 0, v61, vcc
	s_and_b64 vcc, exec, s[12:13]
	global_store_dword v[62:63], v0, off offset:512
	s_cbranch_vccnz .LBB0_530
	v_add_co_u32_e32 v62, vcc, 0x2e00000, v60
	s_nop 1
	v_addc_co_u32_e32 v63, vcc, 0, v61, vcc
	global_store_dword v[62:63], v0, off offset:512
.LBB0_530:
	v_add_co_u32_e32 v62, vcc, 0x3e00000, v58
	s_nop 1
	v_addc_co_u32_e32 v63, vcc, 0, v59, vcc
	s_waitcnt vmcnt(22)
	v_mov_b32_e32 v0, v111
	s_and_b64 vcc, exec, s[10:11]
	s_cbranch_vccnz .LBB0_532
	v_mov_b32_e32 v45, v126
	s_branch .LBB0_533

; __device__ __forceinline__ float bflo(unsigned w) { return __uint_as_float(w << 16); }
; __device__ __forceinline__ float bfhi(unsigned w) { return __uint_as_float(w & 0xffff0000u); }
; __device__ __forceinline__ unsigned pk2(float lo, float hi) { f32x2_t v = {lo, hi}; bf16x2_t b = __builtin_convertvector(v, bf16x2_t); return __builtin_bit_cast(unsigned, b); }
; __device__ __forceinline__ float bflo(unsigned w) { return __uint_as_float(w << 16); }
; __device__ __forceinline__ float bfhi(unsigned w) { return __uint_as_float(w & 0xffff0000u); }
; __device__ __forceinline__ void phase_prep(const Params& P, int l) {
;     ...
;         for (int i = 0; i < 14; ++i) {
;             const int j = lane + 64 * i, col = 2 * j;
;             const unsigned cw = cur[j], pw = hasp ? prv[j] : 0u;
;             const float c0 = bflo(cw), c1 = bfhi(cw), p0 = bflo(pw), p1 = bfhi(pw);
;             float m0 = c0 + (p0 - c0) * mu[col], m1 = c1 + (p1 - c1) * mu[col + 1];
;             if (i < 4) { *(unsigned*)(RB + (size_t)t * 512 + col) = pk2(m0, m1); }
;             else if (i < 8) { *(unsigned*)(KB + (size_t)t * 512 + col - 512) = pk2(m0, m1); }
;             else if (i < 12) { const unsigned w = pk2(m0, m1); *(unsigned*)(VB + (size_t)t * 512 + col - 1024) = w; if (l == 0) *(unsigned*)(VF + (size_t)t * 512 + col - 1024) = w; }
.LBB0_533:
	v_lshlrev_b32_e32 v62, 16, v0
	v_and_b32_e32 v63, 0xffff0000, v0
	v_lshlrev_b32_e32 v64, 16, v45
	v_and_b32_e32 v65, 0xffff0000, v45
	v_pk_add_f32 v[64:65], v[64:65], v[62:63] neg_lo:[0,1] neg_hi:[0,1]
	s_nop 0
	v_pk_fma_f32 v[62:63], v[24:25], v[64:65], v[62:63]
	s_nop 0
	v_cvt_pk_bf16_f32 v0, v62, v63
	v_add_co_u32_e32 v62, vcc, 0x14e00000, v60
	s_nop 1
	v_addc_co_u32_e32 v63, vcc, 0, v61, vcc
	s_and_b64 vcc, exec, s[12:13]
	global_store_dword v[62:63], v0, off offset:768
	s_cbranch_vccnz .LBB0_535
	v_add_co_u32_e32 v60, vcc, 0x2e00000, v60
	s_nop 1
	v_addc_co_u32_e32 v61, vcc, 0, v61, vcc
	global_store_dword v[60:61], v0, off offset:768
.LBB0_535:
	v_add_co_u32_e32 v60, vcc, 0x3e00000, v58
	s_nop 1
	v_addc_co_u32_e32 v61, vcc, 0, v59, vcc
	s_waitcnt vmcnt(21)
	v_mov_b32_e32 v0, v112
	s_and_b64 vcc, exec, s[10:11]
	s_cbranch_vccnz .LBB0_537
	v_mov_b32_e32 v45, v127
	s_branch .LBB0_538

; __device__ __forceinline__ float sigm(float x) { return 1.0f / (1.0f + __expf(-x)); }
; __device__ __forceinline__ unsigned pk2(float lo, float hi) { f32x2_t v = {lo, hi}; bf16x2_t b = __builtin_convertvector(v, bf16x2_t); return __builtin_bit_cast(unsigned, b); }
; __device__ __forceinline__ float sigm(float x) { return 1.0f / (1.0f + __expf(-x)); }
; __device__ __forceinline__ void phase_prep(const Params& P, int l) {
;     ...
;             else {
;                 if (col < 1600) { m0 = tanhf(m0); m1 = tanhf(m1); } else if (col >= 1664) { m0 = sigm(m0); m1 = sigm(m1); }
;                 *(unsigned*)(LIN + (size_t)t * 384 + col - 1536) = pk2(m0, m1);
.LBB0_538:
	v_lshlrev_b32_e32 v60, 16, v0
	v_and_b32_e32 v61, 0xffff0000, v0
	v_lshlrev_b32_e32 v62, 16, v45
	v_and_b32_e32 v63, 0xffff0000, v45
	v_pk_add_f32 v[62:63], v[62:63], v[60:61] neg_lo:[0,1] neg_hi:[0,1]
	s_nop 0
	v_pk_fma_f32 v[60:61], v[26:27], v[62:63], v[60:61]
	s_and_saveexec_b64 s[12:13], s[8:9]
	s_xor_b64 s[12:13], exec, s[12:13]
	s_andn2_saveexec_b64 s[12:13], s[12:13]
	s_cbranch_execz .LBB0_548
	v_cmp_nlt_f32_e64 s[30:31], |v60|, s15
	s_and_saveexec_b64 s[62:63], s[30:31]
	s_xor_b64 s[30:31], exec, s[62:63]
	s_cbranch_execz .LBB0_541
	v_add_f32_e64 v0, |v60|, |v60|
	v_mul_f32_e32 v45, 0x3fb8aa3b, v0
	v_rndne_f32_e32 v62, v45
	s_mov_b32 s62, 0x3fb8aa3b
	v_sub_f32_e32 v63, v45, v62
	v_fma_f32 v45, v0, s62, -v45
	v_fmac_f32_e32 v45, 0x32a5705f, v0
	v_add_f32_e32 v45, v63, v45
	v_cvt_i32_f32_e32 v62, v62
	v_exp_f32_e32 v45, v45
	s_mov_b32 s25, 0xc2ce8ed0
	v_cmp_ngt_f32_e32 vcc, s25, v0
	s_mov_b32 s25, 0x42b17218
	v_ldexp_f32 v45, v45, v62
	v_cndmask_b32_e32 v45, 0, v45, vcc
	v_cmp_nlt_f32_e32 vcc, s25, v0
	s_nop 1
	v_cndmask_b32_e32 v0, v242, v45, vcc
	v_add_f32_e32 v0, 1.0, v0
	v_rcp_f32_e32 v0, v0
	s_nop 0
	v_fma_f32 v0, v0, -2.0, 1.0

; __device__ __forceinline__ float sigm(float x) { return 1.0f / (1.0f + __expf(-x)); }
; __device__ __forceinline__ unsigned pk2(float lo, float hi) { f32x2_t v = {lo, hi}; bf16x2_t b = __builtin_convertvector(v, bf16x2_t); return __builtin_bit_cast(unsigned, b); }
; __device__ __forceinline__ float sigm(float x) { return 1.0f / (1.0f + __expf(-x)); }
; __device__ __forceinline__ void phase_prep(const Params& P, int l) {
;     ...
;             else {
;                 if (col < 1600) { m0 = tanhf(m0); m1 = tanhf(m1); } else if (col >= 1664) { m0 = sigm(m0); m1 = sigm(m1); }
;                 *(unsigned*)(LIN + (size_t)t * 384 + col - 1536) = pk2(m0, m1);
.LBB0_548:
	s_or_b64 exec, exec, s[12:13]
	v_cvt_pk_bf16_f32 v0, v60, v61
	v_lshl_add_u64 v[60:61], s[16:17], 0, v[52:53]
	v_add_co_u32_e32 v62, vcc, 0x18e00000, v60
	s_nop 1
	v_addc_co_u32_e32 v63, vcc, 0, v61, vcc
	global_store_dword v[62:63], v0, off
	v_add_co_u32_e32 v62, vcc, 0x3e00000, v58
	s_nop 1
	v_addc_co_u32_e32 v63, vcc, 0, v59, vcc
	s_waitcnt vmcnt(20)
	v_mov_b32_e32 v0, v113
	s_and_b64 vcc, exec, s[10:11]
	s_cbranch_vccnz .LBB0_550
	v_mov_b32_e32 v45, v128
	s_branch .LBB0_551

; __device__ __forceinline__ float bflo(unsigned w) { return __uint_as_float(w << 16); }
; __device__ __forceinline__ float bfhi(unsigned w) { return __uint_as_float(w & 0xffff0000u); }
; __device__ __forceinline__ float sigm(float x) { return 1.0f / (1.0f + __expf(-x)); }
; __device__ __forceinline__ unsigned pk2(float lo, float hi) { f32x2_t v = {lo, hi}; bf16x2_t b = __builtin_convertvector(v, bf16x2_t); return __builtin_bit_cast(unsigned, b); }
; __device__ __forceinline__ float bflo(unsigned w) { return __uint_as_float(w << 16); }
; __device__ __forceinline__ float bfhi(unsigned w) { return __uint_as_float(w & 0xffff0000u); }
; __device__ __forceinline__ float sigm(float x) { return 1.0f / (1.0f + __expf(-x)); }
; __device__ __forceinline__ void phase_prep(const Params& P, int l) {
;     ...
;                 if (col < 1600) { m0 = tanhf(m0); m1 = tanhf(m1); } else if (col >= 1664) { m0 = sigm(m0); m1 = sigm(m1); }
;                 *(unsigned*)(LIN + (size_t)t * 384 + col - 1536) = pk2(m0, m1);
;             }
;         }
;         if (lane < 16) {
;             unsigned w = 0u;
;             if (l > 0) { const int j = (C1_VRES >> 1) + lane; const unsigned cw = cur[j], pw = hasp ? prv[j] : 0u;
;                 const float c0 = bflo(cw), c1 = bfhi(cw), p0 = bflo(pw), p1 = bfhi(pw);
;                 w = pk2(c0 + (p0 - c0) * vmu[2 * lane], c1 + (p1 - c1) * vmu[2 * lane + 1]); }
;             *(unsigned*)(LIN + (size_t)t * 384 + 256 + 2 * lane) = w;
;         } else {
;             *(unsigned*)(LIN + (size_t)t * 384 + 288 + 2 * (lane - 16)) = 0u;
;         }
.LBB0_551:
	v_lshlrev_b32_e32 v62, 16, v0
	v_lshlrev_b32_e32 v63, 16, v45
	v_and_b32_e32 v0, 0xffff0000, v0
	v_and_b32_e32 v45, 0xffff0000, v45
	v_sub_f32_e32 v45, v45, v0
	v_sub_f32_e32 v63, v63, v62
	v_fmac_f32_e32 v0, v29, v45
	v_fmac_f32_e32 v62, v28, v63
	v_mul_f32_e32 v0, 0xbfb8aa3b, v0
	v_exp_f32_e32 v63, v0
	v_mul_f32_e32 v0, 0xbfb8aa3b, v62
	v_exp_f32_e32 v62, v0
	s_nop 0
	v_pk_add_f32 v[62:63], v[62:63], 1.0 op_sel_hi:[1,0]
	s_nop 0
	v_rcp_f32_e32 v0, v63
	v_rcp_f32_e32 v45, v62
	v_add_co_u32_e32 v62, vcc, 0x18e00000, v60
	v_cvt_pk_bf16_f32 v0, v45, v0
	s_nop 0
	v_addc_co_u32_e32 v63, vcc, 0, v61, vcc
	global_store_dword v[62:63], v0, off offset:256
	s_and_saveexec_b64 s[12:13], s[6:7]
	s_xor_b64 s[12:13], exec, s[12:13]
	s_cbranch_execz .LBB0_553
	v_add_co_u32_e32 v62, vcc, 0x18e00000, v60
	s_nop 1
	v_addc_co_u32_e32 v63, vcc, 0, v61, vcc
	global_store_dword v[62:63], v1, off offset:512
.LBB0_553:
	s_andn2_saveexec_b64 s[12:13], s[12:13]
	s_cbranch_execz .LBB0_560
	s_andn2_b64 vcc, exec, s[38:39]
	v_mov_b32_e32 v0, 0
	s_cbranch_vccnz .LBB0_559
	v_add_co_u32_e32 v62, vcc, 0x3e00000, v58
	s_nop 1
	v_addc_co_u32_e32 v63, vcc, 0, v59, vcc
	s_waitcnt vmcnt(19)
	v_mov_b32_e32 v0, v114
	s_and_b64 vcc, exec, s[10:11]
	s_cbranch_vccnz .LBB0_557
	v_mov_b32_e32 v45, v129
	s_branch .LBB0_558

; __device__ __forceinline__ float bflo(unsigned w) { return __uint_as_float(w << 16); }
; __device__ __forceinline__ float bfhi(unsigned w) { return __uint_as_float(w & 0xffff0000u); }
; __device__ __forceinline__ unsigned f2bf(float f) { unsigned u = __float_as_uint(f); return (u + 0x7fffu + ((u >> 16) & 1u)) >> 16; }
; __device__ __forceinline__ unsigned pk2(float lo, float hi) { f32x2_t v = {lo, hi}; bf16x2_t b = __builtin_convertvector(v, bf16x2_t); return __builtin_bit_cast(unsigned, b); }
; __device__ __forceinline__ float bflo(unsigned w) { return __uint_as_float(w << 16); }
; __device__ __forceinline__ float bfhi(unsigned w) { return __uint_as_float(w & 0xffff0000u); }
; __device__ __forceinline__ void phase_prep(const Params& P, int l) {
;     ...
;         {
;             float c[6]; float s = 0.f;
; #pragma unroll
;             for (int i = 0; i < 3; ++i) { const unsigned w = cur[(C1_CQ >> 1) + lane + 64 * i]; c[2 * i] = bflo(w); c[2 * i + 1] = bfhi(w); s += c[2 * i] * c[2 * i] + c[2 * i + 1] * c[2 * i + 1]; }
;             const float rinv = rsqrtf(wave_sum(s) * (1.f / 384.f) + NORM_EPS);
; #pragma unroll
;             for (int i = 0; i < 3; ++i) { const int cc = 2 * (lane + 64 * i); *(unsigned*)(CQN + (size_t)t * 384 + cc) = pk2(c[2 * i] * rinv * qg[cc], c[2 * i + 1] * rinv * qg[cc + 1]); }
;         }
;         {
;             float c[4]; float s = 0.f;
; #pragma unroll
;             for (int i = 0; i < 2; ++i) { const unsigned w = cur[(C1_CKV >> 1) + lane + 64 * i]; c[2 * i] = bflo(w); c[2 * i + 1] = bfhi(w); s += c[2 * i] * c[2 * i] + c[2 * i + 1] * c[2 * i + 1]; }
;             const float rinv = rsqrtf(wave_sum(s) * (1.f / 256.f) + NORM_EPS);
; #pragma unroll
;             for (int i = 0; i < 2; ++i) { const int cc = 2 * (lane + 64 * i); *(unsigned*)(CKVN + (size_t)t * 256 + cc) = pk2(c[2 * i] * rinv * kvg[cc], c[2 * i + 1] * rinv * kvg[cc + 1]); }
;         }
;         if (lane < 16) {
;             const bf16_t* row = P1 + (size_t)t * NP1 + C1_KR;
;             const float x1 = bf1(row[lane]), x2 = bf1(row[16 + lane]);
;             const float cs = COS[t * 16 + lane], sn = SIN[t * 16 + lane];
;             KROPE[(size_t)t * 32 + lane] = (bf16_t)f2bf(x1 * cs - x2 * sn);
;             KROPE[(size_t)t * 32 + 16 + lane] = (bf16_t)f2bf(x2 * cs + x1 * sn);
;         }
.LBB0_560:
	s_or_b64 exec, exec, s[12:13]
	v_add_co_u32_e32 v62, vcc, 0x3e00000, v58
	s_mov_b32 s10, 0x3b800000
	s_nop 0
	v_addc_co_u32_e32 v63, vcc, 0, v59, vcc
	s_waitcnt vmcnt(14)
	v_mov_b32_e32 v0, v130
	v_add_co_u32_e32 v58, vcc, 0x3e01000, v58
	s_mov_b32 s11, 0x3b2aaaab
	s_nop 0
	v_addc_co_u32_e32 v59, vcc, 0, v59, vcc
	v_lshlrev_b32_e32 v74, 16, v0
	v_and_b32_e32 v75, 0xffff0000, v0
	v_mov_b32_e32 v0, v131
	v_mov_b32_e32 v78, v75
	v_mov_b32_e32 v76, v74
	v_lshlrev_b32_e32 v62, 16, v0
	v_and_b32_e32 v63, 0xffff0000, v0
	v_mov_b32_e32 v0, v132
	v_lshlrev_b32_e32 v66, 16, v0
	v_and_b32_e32 v67, 0xffff0000, v0
	v_mul_f32_e32 v0, v63, v63
	v_pk_fma_f32 v[64:65], v[62:63], v[62:63], v[0:1] op_sel_hi:[1,1,0]
	v_mov_b32_e32 v0, v133
	v_mov_b32_e32 v79, v67
	v_mov_b32_e32 v77, v66
	v_pk_mul_f32 v[78:79], v[78:79], v[78:79]
	v_lshlrev_b32_e32 v80, 16, v0
	v_and_b32_e32 v81, 0xffff0000, v0
	v_mov_b32_e32 v0, v134
	v_mov_b32_e32 v84, v81
	v_pk_fma_f32 v[76:77], v[76:77], v[76:77], v[78:79]
	v_mov_b32_e32 v82, v80
	v_pk_add_f32 v[78:79], v[76:77], v[64:65]
	v_lshl_add_u64 v[64:65], s[16:17], 0, v[48:49]
	v_and_b32_e32 v59, 0xffff0000, v0
	v_lshlrev_b32_e32 v58, 16, v0
	v_mov_b32_e32 v85, v59
	v_mov_b32_e32 v83, v58
	v_pk_mul_f32 v[84:85], v[84:85], v[84:85]
	s_nop 0
	v_pk_fma_f32 v[82:83], v[82:83], v[82:83], v[84:85]
	v_mov_b32_e32 v85, v78
	v_mov_b32_e32 v84, v82
	v_mov_b32_e32 v76, v83
	v_pk_add_f32 v[76:77], v[84:85], v[76:77]
	ds_bpermute_b32 v79, v3, v77
	ds_bpermute_b32 v78, v3, v76
	s_waitcnt lgkmcnt(0)
	v_pk_add_f32 v[76:77], v[76:77], v[78:79]
	ds_bpermute_b32 v79, v68, v77
	ds_bpermute_b32 v78, v68, v76
	s_waitcnt lgkmcnt(0)
	v_pk_add_f32 v[76:77], v[76:77], v[78:79]
	ds_bpermute_b32 v79, v69, v77
	ds_bpermute_b32 v78, v69, v76
	s_waitcnt lgkmcnt(0)
	v_pk_add_f32 v[76:77], v[76:77], v[78:79]
	ds_bpermute_b32 v79, v70, v77
	ds_bpermute_b32 v78, v70, v76
	s_waitcnt lgkmcnt(0)
	v_pk_add_f32 v[76:77], v[76:77], v[78:79]
	ds_bpermute_b32 v79, v71, v77
	ds_bpermute_b32 v78, v71, v76
	s_waitcnt lgkmcnt(0)
	v_pk_add_f32 v[76:77], v[76:77], v[78:79]
	ds_bpermute_b32 v79, v72, v77
	ds_bpermute_b32 v78, v72, v76
	s_waitcnt lgkmcnt(0)
	v_pk_add_f32 v[76:77], v[76:77], v[78:79]
	s_nop 0
	v_pk_fma_f32 v[76:77], v[76:77], s[10:11], v[184:185] op_sel_hi:[1,1,0]
	s_nop 0
	v_mul_f32_e32 v0, 0x4b800000, v77
	v_cmp_gt_f32_e64 s[10:11], s61, v77
	v_cmp_gt_f32_e32 vcc, s61, v76
	s_nop 0
	v_cndmask_b32_e64 v0, v77, v0, s[10:11]
	v_rsq_f32_e32 v0, v0
	s_nop 0
	v_mul_f32_e32 v45, 0x45800000, v0
	v_cndmask_b32_e64 v0, v0, v45, s[10:11]
	v_pk_mul_f32 v[74:75], v[0:1], v[74:75] op_sel_hi:[0,1]
	s_mov_b32 s10, 0x19a00000
	v_pk_mul_f32 v[74:75], v[34:35], v[74:75]
	v_add_co_u32_e64 v60, s[10:11], s10, v60
	v_pk_mul_f32 v[62:63], v[0:1], v[62:63] op_sel_hi:[0,1]
	v_cvt_pk_bf16_f32 v45, v74, v75
	v_addc_co_u32_e64 v61, s[10:11], 0, v61, s[10:11]
	v_pk_mul_f32 v[62:63], v[36:37], v[62:63]
	global_store_dword v[60:61], v45, off
	v_cvt_pk_bf16_f32 v45, v62, v63
	v_pk_mul_f32 v[62:63], v[0:1], v[66:67] op_sel_hi:[0,1]
	v_pk_mul_f32 v[62:63], v[32:33], v[62:63]
	global_store_dword v[60:61], v45, off offset:256
	v_cvt_pk_bf16_f32 v0, v62, v63
	global_store_dword v[60:61], v0, off offset:512
	v_mul_f32_e32 v0, 0x4b800000, v76
	v_cndmask_b32_e32 v0, v76, v0, vcc
	v_rsq_f32_e32 v0, v0
	s_nop 0
	v_mul_f32_e32 v45, 0x45800000, v0
	v_cndmask_b32_e32 v0, v0, v45, vcc
	v_pk_mul_f32 v[60:61], v[0:1], v[80:81] op_sel_hi:[0,1]
	v_pk_mul_f32 v[60:61], v[38:39], v[60:61]
	v_pk_mul_f32 v[58:59], v[0:1], v[58:59] op_sel_hi:[0,1]
	v_cvt_pk_bf16_f32 v45, v60, v61
	v_add_co_u32_e32 v60, vcc, 0x1a600000, v64
	v_pk_mul_f32 v[58:59], v[40:41], v[58:59]
	s_nop 0
	v_addc_co_u32_e32 v61, vcc, 0, v65, vcc
	v_cvt_pk_bf16_f32 v0, v58, v59
	global_store_dword v[60:61], v45, off
	global_store_dword v[60:61], v0, off offset:256
	s_and_saveexec_b64 s[10:11], s[4:5]
	s_cbranch_execz .LBB0_498
	v_lshl_add_u64 v[58:59], s[16:17], 0, v[54:55]
	v_add_co_u32_e32 v58, vcc, 0x3e01000, v58
	s_nop 1
	v_addc_co_u32_e32 v59, vcc, 0, v59, vcc
	global_load_ushort v0, v[58:59], off offset:832
	global_load_ushort v45, v[58:59], off offset:864
	s_waitcnt vmcnt(1)
	v_lshlrev_b32_e32 v0, 16, v0
	s_waitcnt vmcnt(0)
	v_lshlrev_b32_e32 v62, 16, v45
	v_ashrrev_i32_e32 v45, 31, v44
	v_lshlrev_b64 v[58:59], 2, v[44:45]
	v_lshl_add_u64 v[60:61], s[18:19], 0, v[58:59]
	v_lshl_add_u64 v[58:59], s[20:21], 0, v[58:59]
	global_load_dword v45, v[60:61], off
	s_nop 0
	global_load_dword v60, v[58:59], off
	s_waitcnt vmcnt(0)
	v_mul_f32_e32 v58, v60, v62
	v_fma_f32 v58, v45, v0, -v58
	v_bfe_u32 v59, v58, 16, 1
	v_mul_f32_e32 v45, v45, v62
	v_add3_u32 v61, v58, v59, s28
	v_lshl_add_u64 v[58:59], s[16:17], 0, v[46:47]
	v_fmac_f32_e32 v45, v60, v0
	v_add_co_u32_e32 v58, vcc, 0x1ae00000, v58
	v_bfe_u32 v0, v45, 16, 1
	s_nop 0
	v_addc_co_u32_e32 v59, vcc, 0, v59, vcc
	v_add3_u32 v0, v45, v0, s28
	global_store_short_d16_hi v[58:59], v61, off
	global_store_short_d16_hi v[58:59], v0, off offset:32
	s_branch .LBB0_498

; __device__ __forceinline__ void phase_rowwise(const bf16_t* ysrc, const float* hin, float* hout, float wt, const float* g_post, const float* g_pre, bf16_t* xn) {
;     PHASE_IDS;
;     for (int row = gw; row < T; row += 2 * ngw) {
;         const int rowb = row + ngw; const bool two = rowb < T; const int rb = two ? rowb : row;
;         f32x4 ha[4], hb[4]; v2u ya[4], yb[4];
;         { const f32x4* hr = (const f32x4*)(hin + (size_t)row * DM) + lane; const f32x4* hr2 = (const f32x4*)(hin + (size_t)rb * DM) + lane;
;     ...
;                 for (int j = 0; j < 4; ++j) { const f32x4 g = *((const f32x4*)g_post + lane + 64 * j); h[j] = h[j] + y[j] * g * rinv; }
;     ...
;                 for (int j = 0; j < 4; ++j) { const f32x4 g = *((const f32x4*)g_pre + lane + 64 * j); const f32x4 v = h[j] * g * rinv;
.LBB0_1297:
	s_or_b64 exec, exec, s[4:5]
	s_mov_b32 s4, s50
	s_mov_b32 s5, s51
	s_mov_b32 s14, s50
	s_mov_b32 s15, s51
	v_mov_b32_e32 v0, v185
	s_waitcnt lgkmcnt(0)
	s_barrier
	s_nop 0
	v_readfirstlane_b32 s6, v0
	s_ashr_i32 s8, s6, 6
	v_readlane_b32 s6, v253, 7
	s_add_i32 s18, s8, s6
	s_cmpk_gt_i32 s18, 0x3fff
	s_cbranch_scc1 .LBB0_1305
	v_and_b32_e32 v2, 63, v0
	v_lshlrev_b32_e32 v36, 3, v2
	v_mov_b32_e32 v37, v1
	v_lshlrev_b32_e32 v0, 4, v2
	v_lshl_add_u64 v[2:3], s[4:5], 0, v[36:37]
	s_mov_b64 s[6:7], 0x12e00000
	v_lshl_add_u64 v[38:39], v[2:3], 0, s[6:7]
	v_readlane_b32 s6, v255, 3
	v_readlane_b32 s7, v255, 4
	v_and_b32_e32 v2, 64, v241
	v_add_u32_e32 v2, 64, v2
	v_lshl_add_u64 v[40:41], s[6:7], 0, v[0:1]
	v_readlane_b32 s6, v255, 1
	v_readlane_b32 s7, v255, 2
	v_xor_b32_e32 v3, 1, v241
	v_cmp_lt_i32_e32 vcc, v3, v2
	v_lshl_add_u64 v[42:43], s[6:7], 0, v[0:1]
	s_ashr_i32 s6, s8, 31
	v_readlane_b32 s7, v253, 7
	s_add_u32 s10, s7, s8
	v_readlane_b32 s7, v253, 6
	s_addc_u32 s11, s7, s6
	v_cndmask_b32_e32 v3, v241, v3, vcc
	s_lshl_b64 s[6:7], s[10:11], 12
	v_lshlrev_b32_e32 v72, 2, v3
	v_xor_b32_e32 v3, 2, v241
	s_add_u32 s6, s48, s6
	v_readlane_b32 s9, v253, 8
	v_cmp_lt_i32_e32 vcc, v3, v2
	s_addc_u32 s7, s49, s7
	s_add_i32 s12, s9, s8
	v_cndmask_b32_e32 v3, v241, v3, vcc
	s_ashr_i32 s13, s12, 31
	v_lshlrev_b32_e32 v73, 2, v3
	v_xor_b32_e32 v3, 4, v241
	s_lshl_b64 s[8:9], s[12:13], 11
	v_cmp_lt_i32_e32 vcc, v3, v2
	s_add_u32 s8, s14, s8
	s_addc_u32 s9, s15, s9
	v_cndmask_b32_e32 v3, v241, v3, vcc
	s_lshl_b64 s[16:17], s[10:11], 11
	v_lshlrev_b32_e32 v74, 2, v3
	v_xor_b32_e32 v3, 8, v241
	s_add_u32 s4, s4, s16
	v_cmp_lt_i32_e32 vcc, v3, v2
	s_addc_u32 s5, s5, s17
	s_add_u32 s10, s4, 0x12e00400
	v_cndmask_b32_e32 v3, v241, v3, vcc
	v_lshlrev_b32_e32 v75, 2, v3
	v_xor_b32_e32 v3, 16, v241
	s_addc_u32 s11, s5, 0
	s_lshl_b64 s[4:5], s[12:13], 12
	v_cmp_lt_i32_e32 vcc, v3, v2
	s_add_u32 s12, s48, s4
	s_addc_u32 s13, s49, s5
	v_cndmask_b32_e32 v3, v241, v3, vcc
	v_lshlrev_b32_e32 v76, 2, v3
	v_xor_b32_e32 v3, 32, v241
	s_add_u32 s4, s14, s16
	v_cmp_lt_i32_e32 vcc, v3, v2
	s_addc_u32 s5, s15, s17
	s_add_u32 s14, s4, 0x16e00400
	v_cndmask_b32_e32 v2, v241, v3, vcc
	v_lshl_add_u64 v[34:35], s[48:49], 0, v[0:1]
	v_lshlrev_b32_e32 v77, 2, v2
	s_addc_u32 s15, s5, 0
	global_load_dwordx4 v[140:143], v[40:41], off
	global_load_dwordx4 v[144:147], v[40:41], off offset:1024
	global_load_dwordx4 v[148:151], v[40:41], off offset:2048
	global_load_dwordx4 v[152:155], v[40:41], off offset:3072
	v_readlane_b32 s20, v252, 34
	v_readlane_b32 s21, v252, 35
	s_nop 3
	s_andn2_b64 vcc, exec, s[20:21]
	s_cbranch_vccnz .Lrw_nopre_1
	global_load_dwordx4 v[156:159], v[42:43], off
	global_load_dwordx4 v[160:163], v[42:43], off offset:1024
	global_load_dwordx4 v[164:167], v[42:43], off offset:2048
	global_load_dwordx4 v[168:171], v[42:43], off offset:3072

; __device__ __forceinline__ float bflo(unsigned w) { return __uint_as_float(w << 16); }
; __device__ __forceinline__ float bfhi(unsigned w) { return __uint_as_float(w & 0xffff0000u); }
; __device__ __forceinline__ float bflo(unsigned w) { return __uint_as_float(w << 16); }
; __device__ __forceinline__ float bfhi(unsigned w) { return __uint_as_float(w & 0xffff0000u); }
; __device__ __forceinline__ void phase_rowwise(const bf16_t* ysrc, const float* hin, float* hout, float wt, const float* g_post, const float* g_pre, bf16_t* xn) {
;     ...
;     for (int row = gw; row < T; row += 2 * ngw) {
;         const int rowb = row + ngw; const bool two = rowb < T; const int rb = two ? rowb : row;
;         f32x4 ha[4], hb[4]; v2u ya[4], yb[4];
;         { const f32x4* hr = (const f32x4*)(hin + (size_t)row * DM) + lane; const f32x4* hr2 = (const f32x4*)(hin + (size_t)rb * DM) + lane;
; #pragma unroll
;           for (int j = 0; j < 4; ++j) { ha[j] = hr[64 * j]; hb[j] = hr2[64 * j]; }
;           if (ysrc) { const v2u* yr = (const v2u*)(ysrc + (size_t)row * DM) + lane; const v2u* yr2 = (const v2u*)(ysrc + (size_t)rb * DM) + lane;
; #pragma unroll
;             for (int j = 0; j < 4; ++j) { ya[j] = yr[64 * j]; yb[j] = yr2[64 * j]; } } }
; #pragma unroll
;         for (int half = 0; half < 2; ++half) {
;             if (half == 1 && !two) break;
;             const int r = half ? rowb : row;
;             f32x4 h[4];
; #pragma unroll
;             for (int j = 0; j < 4; ++j) h[j] = half ? hb[j] : ha[j];
;             if (ysrc) {
;                 f32x4 y[4]; float s = 0.f;
; #pragma unroll
;                 for (int j = 0; j < 4; ++j) { const v2u w = half ? yb[j] : ya[j]; y[j] = (f32x4){bflo(w.x), bfhi(w.x), bflo(w.y), bfhi(w.y)}; s += (y[j].x * y[j].x + y[j].y * y[j].y) + (y[j].z * y[j].z + y[j].w * y[j].w); }
;                 const float rinv = wt * rsqrtf(wave_sum(s) * (1.f / DM) + NORM_EPS);
; #pragma unroll
;                 for (int j = 0; j < 4; ++j) { const f32x4 g = *((const f32x4*)g_post + lane + 64 * j); h[j] = h[j] + y[j] * g * rinv; }
;             }
;             f32x4* ho = (f32x4*)(hout + (size_t)r * DM) + lane;
; #pragma unroll
;             for (int j = 0; j < 4; ++j) ho[64 * j] = h[j];
.LBB0_1300:
	s_add_i32 s19, s24, s18
	s_cmpk_lt_i32 s19, 0x4000
	s_cselect_b64 s[16:17], -1, 0
	s_and_b64 s[4:5], s[16:17], exec
	s_cselect_b32 s4, s19, s18
	s_ashr_i32 s5, s4, 31
	s_lshl_b64 s[20:21], s[4:5], 12
	v_lshl_add_u64 v[52:53], s[6:7], 0, v[0:1]
	v_lshl_add_u64 v[2:3], v[34:35], 0, s[20:21]
	v_lshl_add_u64 v[48:49], s[10:11], 0, v[36:37]
	s_lshl_b64 s[4:5], s[4:5], 11
	global_load_dwordx4 v[18:21], v[52:53], off
	global_load_dwordx4 v[14:17], v[2:3], off
	global_load_dwordx4 v[22:25], v[52:53], off offset:1024
	global_load_dwordx4 v[10:13], v[2:3], off offset:1024
	global_load_dwordx4 v[26:29], v[52:53], off offset:2048
	global_load_dwordx4 v[6:9], v[2:3], off offset:2048
	global_load_dwordx4 v[30:33], v[52:53], off offset:3072
	s_nop 0
	global_load_dwordx4 v[2:5], v[2:3], off offset:3072
	v_lshl_add_u64 v[54:55], v[38:39], 0, s[4:5]
	global_load_dwordx2 v[56:57], v[48:49], off offset:-1024
	global_load_dwordx2 v[50:51], v[54:55], off
	global_load_dwordx2 v[58:59], v[48:49], off offset:-512
	global_load_dwordx2 v[46:47], v[54:55], off offset:512
	global_load_dwordx2 v[62:63], v[48:49], off
	global_load_dwordx2 v[44:45], v[54:55], off offset:1024
	global_load_dwordx2 v[78:79], v[48:49], off offset:512
	s_nop 0
	global_load_dwordx2 v[48:49], v[54:55], off offset:1536
	v_readlane_b32 s20, v252, 34
	v_readlane_b32 s21, v252, 35
	s_waitcnt vmcnt(7)
	v_and_b32_e32 v71, 0xffff0000, v57
	v_and_b32_e32 v69, 0xffff0000, v56
	v_lshlrev_b32_e32 v70, 16, v57
	v_mul_f32_e32 v54, v71, v71
	s_waitcnt vmcnt(5)
	v_and_b32_e32 v67, 0xffff0000, v59
	v_and_b32_e32 v66, 0xffff0000, v58
	v_lshlrev_b32_e32 v68, 16, v56
	v_pk_fma_f32 v[80:81], v[70:71], v[70:71], v[54:55] op_sel_hi:[1,1,0]
	v_lshlrev_b32_e32 v65, 16, v59
	v_lshlrev_b32_e32 v64, 16, v58
	v_pk_mul_f32 v[54:55], v[66:67], v[66:67]
	s_waitcnt vmcnt(1)
	v_and_b32_e32 v57, 0xffff0000, v78
	v_mul_f32_e32 v56, v69, v69
	v_pk_fma_f32 v[82:83], v[64:65], v[64:65], v[54:55]
	v_lshlrev_b32_e32 v59, 16, v78
	v_lshlrev_b32_e32 v54, 16, v79
	v_and_b32_e32 v55, 0xffff0000, v79
	v_pk_fma_f32 v[78:79], v[68:69], v[68:69], v[56:57] op_sel_hi:[1,1,0]
	v_mov_b32_e32 v84, v80
	v_mov_b32_e32 v58, v78
	v_mov_b32_e32 v85, v59
	v_pk_add_f32 v[78:79], v[78:79], v[80:81]
	v_pk_mul_f32 v[80:81], v[58:59], v[84:85]
	v_and_b32_e32 v61, 0xffff0000, v62
	v_mul_f32_e32 v86, v57, v57
	v_mov_b32_e32 v79, v81
	v_pk_add_f32 v[80:81], v[82:83], v[82:83] op_sel:[0,1] op_sel_hi:[1,0]
	v_lshlrev_b32_e32 v60, 16, v62
	v_lshlrev_b32_e32 v62, 16, v63
	v_and_b32_e32 v63, 0xffff0000, v63
	v_mov_b32_e32 v81, v86
	v_mul_f32_e32 v56, v61, v61
	v_pk_add_f32 v[78:79], v[78:79], v[80:81]
	v_pk_fma_f32 v[80:81], v[60:61], v[60:61], v[56:57] op_sel_hi:[1,1,0]
	v_mul_f32_e32 v56, v63, v63
	v_mul_f32_e32 v87, v54, v54
	v_mul_f32_e32 v88, v55, v55
	v_pk_fma_f32 v[82:83], v[62:63], v[62:63], v[56:57] op_sel_hi:[1,1,0]
	v_mov_b32_e32 v81, v87
	v_mov_b32_e32 v83, v88
	v_pk_add_f32 v[80:81], v[80:81], v[82:83]
	s_nop 0
	v_pk_add_f32 v[78:79], v[78:79], v[80:81]
	s_nop 0
	v_add_f32_e32 v56, v78, v79
	v_mov_b64_e32 v[78:79], v[140:141]
	v_mov_b64_e32 v[80:81], v[142:143]
	ds_bpermute_b32 v58, v72, v56
	s_waitcnt lgkmcnt(0)
	v_add_f32_e32 v56, v56, v58
	ds_bpermute_b32 v58, v73, v56
	s_waitcnt lgkmcnt(0)
	v_add_f32_e32 v56, v56, v58
	ds_bpermute_b32 v58, v74, v56
	s_waitcnt lgkmcnt(0)
	v_add_f32_e32 v56, v56, v58
	ds_bpermute_b32 v58, v75, v56
	s_waitcnt lgkmcnt(0)
	v_add_f32_e32 v56, v56, v58
	ds_bpermute_b32 v58, v76, v56
	s_waitcnt lgkmcnt(0)
	v_add_f32_e32 v56, v56, v58
	ds_bpermute_b32 v58, v77, v56
	s_waitcnt lgkmcnt(0)
	v_add_f32_e32 v56, v56, v58
	v_fmamk_f32 v56, v56, 0x3a800000, v184
	v_cmp_gt_f32_e32 vcc, s61, v56
	v_mul_f32_e32 v58, 0x4b800000, v56
	s_waitcnt vmcnt(0)
	v_pk_mul_f32 v[68:69], v[78:79], v[68:69]
	v_cndmask_b32_e32 v56, v56, v58, vcc
	v_rsq_f32_e32 v56, v56
	v_pk_mul_f32 v[70:71], v[80:81], v[70:71]
	v_mov_b32_e32 v79, v66
	v_mov_b32_e32 v66, v65
	v_mul_f32_e32 v58, 0x45800000, v56
	v_cndmask_b32_e32 v58, v56, v58, vcc
	v_pk_fma_f32 v[20:21], v[70:71], v[58:59], v[20:21] op_sel_hi:[1,0,1]
	v_pk_fma_f32 v[18:19], v[68:69], v[58:59], v[18:19] op_sel_hi:[1,0,1]
	v_mov_b64_e32 v[68:69], v[144:145]
	v_mov_b64_e32 v[70:71], v[146:147]
	v_mov_b32_e32 v78, v64
	v_mov_b32_e32 v56, v59
	s_andn2_b64 vcc, exec, s[20:21]
	v_pk_mul_f32 v[64:65], v[70:71], v[66:67]
	s_nop 0
	v_pk_fma_f32 v[24:25], v[64:65], v[58:59], v[24:25] op_sel_hi:[1,0,1]
	v_mov_b64_e32 v[64:65], v[148:149]
	v_mov_b64_e32 v[66:67], v[150:151]
	v_pk_mul_f32 v[68:69], v[68:69], v[78:79]
	v_pk_mul_f32 v[60:61], v[64:65], v[60:61]
	v_pk_mul_f32 v[62:63], v[66:67], v[62:63]
	v_pk_fma_f32 v[26:27], v[60:61], v[58:59], v[26:27] op_sel_hi:[1,0,1]
	v_pk_fma_f32 v[28:29], v[62:63], v[58:59], v[28:29] op_sel_hi:[1,0,1]
	v_mov_b64_e32 v[60:61], v[152:153]
	v_mov_b64_e32 v[62:63], v[154:155]
	v_pk_fma_f32 v[22:23], v[68:69], v[58:59], v[22:23] op_sel_hi:[1,0,1]
	v_pk_mul_f32 v[56:57], v[56:57], v[60:61]
	v_pk_mul_f32 v[54:55], v[54:55], v[62:63]
	v_pk_fma_f32 v[30:31], v[56:57], v[58:59], v[30:31] op_sel_hi:[1,0,1]
	v_pk_fma_f32 v[32:33], v[54:55], v[58:59], v[32:33] op_sel_hi:[1,0,1]
	global_store_dwordx4 v[52:53], v[18:21], off
	global_store_dwordx4 v[52:53], v[22:25], off offset:1024
	global_store_dwordx4 v[52:53], v[26:29], off offset:2048
	global_store_dwordx4 v[52:53], v[30:33], off offset:3072
	v_cndmask_b32_e64 v52, 0, 1, s[20:21]
	v_cmp_ne_u32_e64 s[4:5], 1, v52
	s_cbranch_vccnz .LBB0_1302
; __device__ __forceinline__ float bflo(unsigned w) { return __uint_as_float(w << 16); }
; __device__ __forceinline__ float bfhi(unsigned w) { return __uint_as_float(w & 0xffff0000u); }
; __device__ __forceinline__ unsigned pk2(float lo, float hi) { f32x2_t v = {lo, hi}; bf16x2_t b = __builtin_convertvector(v, bf16x2_t); return __builtin_bit_cast(unsigned, b); }
; __device__ __forceinline__ float bflo(unsigned w) { return __uint_as_float(w << 16); }
; __device__ __forceinline__ float bfhi(unsigned w) { return __uint_as_float(w & 0xffff0000u); }
; __device__ __forceinline__ void phase_rowwise(const bf16_t* ysrc, const float* hin, float* hout, float wt, const float* g_post, const float* g_pre, bf16_t* xn) {
;     ...
;             if (ysrc) {
;                 f32x4 y[4]; float s = 0.f;
; #pragma unroll
;                 for (int j = 0; j < 4; ++j) { const v2u w = half ? yb[j] : ya[j]; y[j] = (f32x4){bflo(w.x), bfhi(w.x), bflo(w.y), bfhi(w.y)}; s += (y[j].x * y[j].x + y[j].y * y[j].y) + (y[j].z * y[j].z + y[j].w * y[j].w); }
;                 const float rinv = wt * rsqrtf(wave_sum(s) * (1.f / DM) + NORM_EPS);
; #pragma unroll
;                 for (int j = 0; j < 4; ++j) { const f32x4 g = *((const f32x4*)g_post + lane + 64 * j); h[j] = h[j] + y[j] * g * rinv; }
;             }
;             f32x4* ho = (f32x4*)(hout + (size_t)r * DM) + lane;
; #pragma unroll
;             for (int j = 0; j < 4; ++j) ho[64 * j] = h[j];
;             if (g_pre) {
;                 float s = 0.f;
; #pragma unroll
;                 for (int j = 0; j < 4; ++j) s += (h[j].x * h[j].x + h[j].y * h[j].y) + (h[j].z * h[j].z + h[j].w * h[j].w);
;                 const float rinv = rsqrtf(wave_sum(s) * (1.f / DM) + NORM_EPS);
;                 unsigned long long* o8 = (unsigned long long*)(xn + (size_t)r * DM) + lane;
; #pragma unroll
;                 for (int j = 0; j < 4; ++j) { const f32x4 g = *((const f32x4*)g_pre + lane + 64 * j); const f32x4 v = h[j] * g * rinv;
;                     o8[64 * j] = (unsigned long long)pk2(v.x, v.y) | ((unsigned long long)pk2(v.z, v.w) << 32); }
	v_pk_mul_f32 v[52:53], v[20:21], v[20:21]
	v_pk_mul_f32 v[54:55], v[18:19], v[18:19]
	s_nop 0
	v_pk_mov_b32 v[56:57], v[54:55], v[52:53] op_sel:[1,0]
	v_mov_b32_e32 v55, v53
	v_pk_add_f32 v[52:53], v[56:57], v[54:55]
	v_pk_mul_f32 v[54:55], v[24:25], v[24:25]
	v_pk_add_f32 v[52:53], v[52:53], v[52:53] op_sel_hi:[0,1]
	v_pk_mul_f32 v[56:57], v[22:23], v[22:23]
	v_mul_f32_e32 v52, v26, v26
	v_pk_mov_b32 v[58:59], v[56:57], v[54:55] op_sel:[1,0]
	v_mov_b32_e32 v57, v55
	v_pk_add_f32 v[54:55], v[58:59], v[56:57]
	v_pk_fma_f32 v[56:57], v[26:27], v[26:27], v[52:53] op_sel_hi:[1,1,0]
	v_mul_f32_e32 v52, v28, v28
	v_pk_add_f32 v[54:55], v[54:55], v[54:55] op_sel_hi:[0,1]
	v_pk_fma_f32 v[58:59], v[28:29], v[28:29], v[52:53] op_sel_hi:[1,1,0]
	v_mul_f32_e32 v56, v30, v30
	v_mul_f32_e32 v58, v31, v31
	v_mul_f32_e32 v52, v32, v32
	v_mul_f32_e32 v54, v33, v33
	v_pk_add_f32 v[56:57], v[56:57], v[58:59]
	v_pk_add_f32 v[52:53], v[52:53], v[54:55]
	s_nop 0
	v_pk_add_f32 v[52:53], v[56:57], v[52:53]
	v_mov_b64_e32 v[56:57], v[156:157]
	v_mov_b64_e32 v[58:59], v[158:159]
	v_add_f32_e32 v52, v52, v53
	ds_bpermute_b32 v53, v72, v52
	s_waitcnt lgkmcnt(0)
	v_add_f32_e32 v52, v52, v53
	ds_bpermute_b32 v53, v73, v52
	s_waitcnt lgkmcnt(0)
	v_add_f32_e32 v52, v52, v53
	ds_bpermute_b32 v53, v74, v52
	s_waitcnt lgkmcnt(0)
	v_add_f32_e32 v52, v52, v53
	ds_bpermute_b32 v53, v75, v52
	s_waitcnt lgkmcnt(0)
	v_add_f32_e32 v52, v52, v53
	ds_bpermute_b32 v53, v76, v52
	s_waitcnt lgkmcnt(0)
	v_add_f32_e32 v52, v52, v53
	ds_bpermute_b32 v53, v77, v52
	s_waitcnt lgkmcnt(0)
	v_add_f32_e32 v52, v52, v53
	v_fmamk_f32 v52, v52, 0x3a800000, v184
	v_cmp_gt_f32_e32 vcc, s61, v52
	v_mul_f32_e32 v53, 0x4b800000, v52
	v_pk_mul_f32 v[20:21], v[20:21], v[58:59]
	v_cndmask_b32_e32 v52, v52, v53, vcc
	v_rsq_f32_e32 v52, v52
	v_pk_mul_f32 v[18:19], v[18:19], v[56:57]
	v_mul_f32_e32 v53, 0x45800000, v52
	v_cndmask_b32_e32 v54, v52, v53, vcc
	v_pk_mul_f32 v[20:21], v[20:21], v[54:55] op_sel_hi:[1,0]
	v_pk_mul_f32 v[18:19], v[18:19], v[54:55] op_sel_hi:[1,0]
	v_lshl_add_u64 v[52:53], s[14:15], 0, v[36:37]
	v_cvt_pk_bf16_f32 v18, v18, v19
	v_cvt_pk_bf16_f32 v19, v20, v21
	global_store_dwordx2 v[52:53], v[18:19], off offset:-1024
	v_mov_b64_e32 v[18:19], v[160:161]
	v_mov_b64_e32 v[20:21], v[162:163]
	v_pk_mul_f32 v[20:21], v[24:25], v[20:21]
	v_pk_mul_f32 v[18:19], v[22:23], v[18:19]
	v_pk_mul_f32 v[20:21], v[20:21], v[54:55] op_sel_hi:[1,0]
	v_pk_mul_f32 v[18:19], v[18:19], v[54:55] op_sel_hi:[1,0]
	s_nop 0
	v_cvt_pk_bf16_f32 v18, v18, v19
	v_cvt_pk_bf16_f32 v19, v20, v21
	global_store_dwordx2 v[52:53], v[18:19], off offset:-512
	v_mov_b64_e32 v[18:19], v[164:165]
	v_mov_b64_e32 v[20:21], v[166:167]
	v_pk_mul_f32 v[20:21], v[28:29], v[20:21]
	v_pk_mul_f32 v[18:19], v[26:27], v[18:19]
	v_pk_mul_f32 v[20:21], v[20:21], v[54:55] op_sel_hi:[1,0]
	v_pk_mul_f32 v[18:19], v[18:19], v[54:55] op_sel_hi:[1,0]
	s_nop 0
	v_cvt_pk_bf16_f32 v18, v18, v19
	v_cvt_pk_bf16_f32 v19, v20, v21
	global_store_dwordx2 v[52:53], v[18:19], off
	v_mov_b64_e32 v[18:19], v[168:169]
	v_mov_b64_e32 v[20:21], v[170:171]
	v_pk_mul_f32 v[20:21], v[32:33], v[20:21]
	v_pk_mul_f32 v[18:19], v[30:31], v[18:19]
	v_pk_mul_f32 v[20:21], v[20:21], v[54:55] op_sel_hi:[1,0]
	v_pk_mul_f32 v[18:19], v[18:19], v[54:55] op_sel_hi:[1,0]
	s_nop 0
	v_cvt_pk_bf16_f32 v18, v18, v19
	v_cvt_pk_bf16_f32 v19, v20, v21
	global_store_dwordx2 v[52:53], v[18:19], off offset:512
.LBB0_1302:
	s_andn2_b64 vcc, exec, s[16:17]
	s_cbranch_vccnz .LBB0_1299
	v_lshlrev_b32_e32 v32, 16, v50
	v_and_b32_e32 v33, 0xffff0000, v50
	v_lshlrev_b32_e32 v50, 16, v51
	v_and_b32_e32 v51, 0xffff0000, v51
	v_mul_f32_e32 v18, v51, v51
	v_and_b32_e32 v31, 0xffff0000, v47
	v_and_b32_e32 v30, 0xffff0000, v46
	v_and_b32_e32 v21, 0xffff0000, v48
	v_mul_f32_e32 v20, v33, v33
	v_pk_fma_f32 v[52:53], v[50:51], v[50:51], v[18:19] op_sel_hi:[1,1,0]
	v_lshlrev_b32_e32 v29, 16, v47
	v_lshlrev_b32_e32 v28, 16, v46
	v_pk_mul_f32 v[18:19], v[30:31], v[30:31]
	v_lshlrev_b32_e32 v24, 16, v44
	v_and_b32_e32 v25, 0xffff0000, v44
	v_lshlrev_b32_e32 v26, 16, v45
	v_and_b32_e32 v27, 0xffff0000, v45
	v_lshlrev_b32_e32 v23, 16, v48
	v_pk_fma_f32 v[44:45], v[32:33], v[32:33], v[20:21] op_sel_hi:[1,1,0]
	v_pk_fma_f32 v[46:47], v[28:29], v[28:29], v[18:19]
	v_lshlrev_b32_e32 v18, 16, v49
	v_and_b32_e32 v19, 0xffff0000, v49
	v_mov_b32_e32 v22, v44
	v_mov_b32_e32 v48, v52
	v_mov_b32_e32 v49, v23
	v_mul_f32_e32 v54, v21, v21
	v_pk_add_f32 v[44:45], v[44:45], v[52:53]
	v_pk_mul_f32 v[48:49], v[22:23], v[48:49]
	v_pk_add_f32 v[46:47], v[46:47], v[46:47] op_sel:[0,1] op_sel_hi:[1,0]
	v_mov_b32_e32 v45, v49
	v_mov_b32_e32 v47, v54
	v_mul_f32_e32 v20, v25, v25
	v_pk_add_f32 v[44:45], v[44:45], v[46:47]
	v_pk_fma_f32 v[46:47], v[24:25], v[24:25], v[20:21] op_sel_hi:[1,1,0]
	v_mul_f32_e32 v20, v27, v27
	v_mul_f32_e32 v55, v18, v18
	v_mul_f32_e32 v56, v19, v19
	v_pk_fma_f32 v[48:49], v[26:27], v[26:27], v[20:21] op_sel_hi:[1,1,0]
	v_mov_b32_e32 v47, v55
	v_mov_b32_e32 v49, v56
	v_pk_add_f32 v[46:47], v[46:47], v[48:49]
	s_nop 0
	v_pk_add_f32 v[44:45], v[44:45], v[46:47]
	s_nop 0
	v_add_f32_e32 v20, v44, v45
	v_mov_b64_e32 v[44:45], v[140:141]
	v_mov_b64_e32 v[46:47], v[142:143]
	ds_bpermute_b32 v22, v72, v20
	s_waitcnt lgkmcnt(0)
	v_add_f32_e32 v20, v20, v22
	ds_bpermute_b32 v22, v73, v20
	s_waitcnt lgkmcnt(0)
	v_add_f32_e32 v20, v20, v22
	ds_bpermute_b32 v22, v74, v20
	s_waitcnt lgkmcnt(0)
	v_add_f32_e32 v20, v20, v22
	ds_bpermute_b32 v22, v75, v20
	s_waitcnt lgkmcnt(0)
; __device__ __forceinline__ float bflo(unsigned w) { return __uint_as_float(w << 16); }
; __device__ __forceinline__ float bfhi(unsigned w) { return __uint_as_float(w & 0xffff0000u); }
; __device__ __forceinline__ unsigned pk2(float lo, float hi) { f32x2_t v = {lo, hi}; bf16x2_t b = __builtin_convertvector(v, bf16x2_t); return __builtin_bit_cast(unsigned, b); }
; __device__ __forceinline__ float bflo(unsigned w) { return __uint_as_float(w << 16); }
; __device__ __forceinline__ float bfhi(unsigned w) { return __uint_as_float(w & 0xffff0000u); }
; __device__ __forceinline__ void phase_rowwise(const bf16_t* ysrc, const float* hin, float* hout, float wt, const float* g_post, const float* g_pre, bf16_t* xn) {
;     ...
;             if (ysrc) {
;                 f32x4 y[4]; float s = 0.f;
; #pragma unroll
;                 for (int j = 0; j < 4; ++j) { const v2u w = half ? yb[j] : ya[j]; y[j] = (f32x4){bflo(w.x), bfhi(w.x), bflo(w.y), bfhi(w.y)}; s += (y[j].x * y[j].x + y[j].y * y[j].y) + (y[j].z * y[j].z + y[j].w * y[j].w); }
;                 const float rinv = wt * rsqrtf(wave_sum(s) * (1.f / DM) + NORM_EPS);
; #pragma unroll
;                 for (int j = 0; j < 4; ++j) { const f32x4 g = *((const f32x4*)g_post + lane + 64 * j); h[j] = h[j] + y[j] * g * rinv; }
;             }
;             f32x4* ho = (f32x4*)(hout + (size_t)r * DM) + lane;
; #pragma unroll
;             for (int j = 0; j < 4; ++j) ho[64 * j] = h[j];
;             if (g_pre) {
;                 float s = 0.f;
; #pragma unroll
;                 for (int j = 0; j < 4; ++j) s += (h[j].x * h[j].x + h[j].y * h[j].y) + (h[j].z * h[j].z + h[j].w * h[j].w);
;                 const float rinv = rsqrtf(wave_sum(s) * (1.f / DM) + NORM_EPS);
;                 unsigned long long* o8 = (unsigned long long*)(xn + (size_t)r * DM) + lane;
; #pragma unroll
;                 for (int j = 0; j < 4; ++j) { const f32x4 g = *((const f32x4*)g_pre + lane + 64 * j); const f32x4 v = h[j] * g * rinv;
;                     o8[64 * j] = (unsigned long long)pk2(v.x, v.y) | ((unsigned long long)pk2(v.z, v.w) << 32); }
	v_add_f32_e32 v20, v20, v22
	ds_bpermute_b32 v22, v76, v20
	s_waitcnt lgkmcnt(0)
	v_add_f32_e32 v20, v20, v22
	ds_bpermute_b32 v22, v77, v20
	s_waitcnt lgkmcnt(0)
	v_add_f32_e32 v20, v20, v22
	v_fmamk_f32 v20, v20, 0x3a800000, v184
	v_cmp_gt_f32_e32 vcc, s61, v20
	v_mul_f32_e32 v22, 0x4b800000, v20
	v_pk_mul_f32 v[32:33], v[44:45], v[32:33]
	v_cndmask_b32_e32 v20, v20, v22, vcc
	v_rsq_f32_e32 v20, v20
	v_pk_mul_f32 v[44:45], v[46:47], v[50:51]
	v_mul_f32_e32 v22, 0x45800000, v20
	v_cndmask_b32_e32 v22, v20, v22, vcc
	v_pk_fma_f32 v[16:17], v[44:45], v[22:23], v[16:17] op_sel_hi:[1,0,1]
	v_mov_b64_e32 v[44:45], v[144:145]
	v_mov_b64_e32 v[46:47], v[146:147]
	v_pk_fma_f32 v[14:15], v[32:33], v[22:23], v[14:15] op_sel_hi:[1,0,1]
	v_mov_b32_e32 v33, v30
	v_mov_b32_e32 v30, v29
	v_mov_b32_e32 v32, v28
	v_mov_b32_e32 v20, v23
	s_and_b64 vcc, exec, s[4:5]
	v_pk_mul_f32 v[28:29], v[46:47], v[30:31]
	s_nop 0
	v_pk_fma_f32 v[12:13], v[28:29], v[22:23], v[12:13] op_sel_hi:[1,0,1]
	v_mov_b64_e32 v[28:29], v[148:149]
	v_mov_b64_e32 v[30:31], v[150:151]
	v_pk_mul_f32 v[32:33], v[44:45], v[32:33]
	v_pk_mul_f32 v[24:25], v[28:29], v[24:25]
	v_pk_mul_f32 v[26:27], v[30:31], v[26:27]
	v_pk_fma_f32 v[6:7], v[24:25], v[22:23], v[6:7] op_sel_hi:[1,0,1]
	v_pk_fma_f32 v[8:9], v[26:27], v[22:23], v[8:9] op_sel_hi:[1,0,1]
	v_mov_b64_e32 v[24:25], v[152:153]
	v_mov_b64_e32 v[26:27], v[154:155]
	v_pk_fma_f32 v[10:11], v[32:33], v[22:23], v[10:11] op_sel_hi:[1,0,1]
	v_pk_mul_f32 v[20:21], v[20:21], v[24:25]
	v_pk_mul_f32 v[18:19], v[18:19], v[26:27]
	v_pk_fma_f32 v[2:3], v[20:21], v[22:23], v[2:3] op_sel_hi:[1,0,1]
	v_pk_fma_f32 v[4:5], v[18:19], v[22:23], v[4:5] op_sel_hi:[1,0,1]
	v_lshl_add_u64 v[18:19], s[12:13], 0, v[0:1]
	global_store_dwordx4 v[18:19], v[14:17], off
	global_store_dwordx4 v[18:19], v[10:13], off offset:1024
	global_store_dwordx4 v[18:19], v[6:9], off offset:2048
	global_store_dwordx4 v[18:19], v[2:5], off offset:3072
	s_cbranch_vccnz .LBB0_1299
	v_pk_mul_f32 v[18:19], v[16:17], v[16:17]
	v_pk_mul_f32 v[20:21], v[14:15], v[14:15]
	s_mov_b32 s4, 0x16e00000
	v_pk_mov_b32 v[22:23], v[20:21], v[18:19] op_sel:[1,0]
	v_mov_b32_e32 v21, v19
	v_pk_add_f32 v[18:19], v[22:23], v[20:21]
	v_pk_mul_f32 v[20:21], v[12:13], v[12:13]
	v_pk_add_f32 v[18:19], v[18:19], v[18:19] op_sel_hi:[0,1]
	v_pk_mul_f32 v[22:23], v[10:11], v[10:11]
	v_mul_f32_e32 v18, v6, v6
	v_pk_mov_b32 v[24:25], v[22:23], v[20:21] op_sel:[1,0]
	v_mov_b32_e32 v23, v21
	v_pk_add_f32 v[20:21], v[24:25], v[22:23]
	v_pk_fma_f32 v[22:23], v[6:7], v[6:7], v[18:19] op_sel_hi:[1,1,0]
	v_mul_f32_e32 v18, v8, v8
	v_pk_add_f32 v[20:21], v[20:21], v[20:21] op_sel_hi:[0,1]
	v_pk_fma_f32 v[24:25], v[8:9], v[8:9], v[18:19] op_sel_hi:[1,1,0]
	v_mul_f32_e32 v22, v2, v2
	v_mul_f32_e32 v24, v3, v3
	v_mul_f32_e32 v18, v4, v4
	v_mul_f32_e32 v20, v5, v5
	v_pk_add_f32 v[22:23], v[22:23], v[24:25]
	v_pk_add_f32 v[18:19], v[18:19], v[20:21]
	v_lshl_add_u64 v[20:21], s[8:9], 0, v[36:37]
	v_pk_add_f32 v[18:19], v[22:23], v[18:19]
	v_mov_b64_e32 v[22:23], v[156:157]
	v_mov_b64_e32 v[24:25], v[158:159]
	v_add_f32_e32 v18, v18, v19
	ds_bpermute_b32 v19, v72, v18
	s_waitcnt lgkmcnt(0)
	v_add_f32_e32 v18, v18, v19
	ds_bpermute_b32 v19, v73, v18
	s_waitcnt lgkmcnt(0)
	v_add_f32_e32 v18, v18, v19
	ds_bpermute_b32 v19, v74, v18
	s_waitcnt lgkmcnt(0)
	v_add_f32_e32 v18, v18, v19
	ds_bpermute_b32 v19, v75, v18
	s_waitcnt lgkmcnt(0)
	v_add_f32_e32 v18, v18, v19
	ds_bpermute_b32 v19, v76, v18
	s_waitcnt lgkmcnt(0)
	v_add_f32_e32 v18, v18, v19
	ds_bpermute_b32 v19, v77, v18
	s_waitcnt lgkmcnt(0)
	v_add_f32_e32 v18, v18, v19
	v_fmamk_f32 v18, v18, 0x3a800000, v184
	v_cmp_gt_f32_e32 vcc, s61, v18
	v_mul_f32_e32 v19, 0x4b800000, v18
	v_pk_mul_f32 v[16:17], v[16:17], v[24:25]
	v_cndmask_b32_e32 v18, v18, v19, vcc
	v_rsq_f32_e32 v18, v18
	v_pk_mul_f32 v[14:15], v[14:15], v[22:23]
	v_mul_f32_e32 v19, 0x45800000, v18
	v_cndmask_b32_e32 v18, v18, v19, vcc
	v_pk_mul_f32 v[16:17], v[16:17], v[18:19] op_sel_hi:[1,0]
	v_pk_mul_f32 v[14:15], v[14:15], v[18:19] op_sel_hi:[1,0]
	v_add_co_u32_e32 v20, vcc, s4, v20
	v_cvt_pk_bf16_f32 v14, v14, v15
	v_cvt_pk_bf16_f32 v15, v16, v17
	v_addc_co_u32_e32 v21, vcc, 0, v21, vcc
	global_store_dwordx2 v[20:21], v[14:15], off
	v_mov_b64_e32 v[14:15], v[160:161]
	v_mov_b64_e32 v[16:17], v[162:163]
	v_pk_mul_f32 v[12:13], v[12:13], v[16:17]
	v_pk_mul_f32 v[10:11], v[10:11], v[14:15]
	v_pk_mul_f32 v[12:13], v[12:13], v[18:19] op_sel_hi:[1,0]
	v_pk_mul_f32 v[10:11], v[10:11], v[18:19] op_sel_hi:[1,0]
	s_nop 0
	v_cvt_pk_bf16_f32 v10, v10, v11
	v_cvt_pk_bf16_f32 v11, v12, v13
	global_store_dwordx2 v[20:21], v[10:11], off offset:512
	v_mov_b64_e32 v[10:11], v[164:165]
	v_mov_b64_e32 v[12:13], v[166:167]
	v_pk_mul_f32 v[8:9], v[8:9], v[12:13]
	v_pk_mul_f32 v[6:7], v[6:7], v[10:11]
	v_pk_mul_f32 v[8:9], v[8:9], v[18:19] op_sel_hi:[1,0]
	v_pk_mul_f32 v[6:7], v[6:7], v[18:19] op_sel_hi:[1,0]
	s_nop 0
	v_cvt_pk_bf16_f32 v6, v6, v7
	v_cvt_pk_bf16_f32 v7, v8, v9
	global_store_dwordx2 v[20:21], v[6:7], off offset:1024
	v_mov_b64_e32 v[6:7], v[168:169]
	v_mov_b64_e32 v[8:9], v[170:171]
	v_pk_mul_f32 v[4:5], v[4:5], v[8:9]
	v_pk_mul_f32 v[2:3], v[2:3], v[6:7]
	v_pk_mul_f32 v[4:5], v[4:5], v[18:19] op_sel_hi:[1,0]
	v_pk_mul_f32 v[2:3], v[2:3], v[18:19] op_sel_hi:[1,0]
	s_nop 0
	v_cvt_pk_bf16_f32 v2, v2, v3
	v_cvt_pk_bf16_f32 v3, v4, v5
	global_store_dwordx2 v[20:21], v[2:3], off offset:1536
	s_branch .LBB0_1299

; __device__ __forceinline__ void phase_rowwise(const bf16_t* ysrc, const float* hin, float* hout, float wt, const float* g_post, const float* g_pre, bf16_t* xn) {
;     PHASE_IDS;
;     for (int row = gw; row < T; row += 2 * ngw) {
;         const int rowb = row + ngw; const bool two = rowb < T; const int rb = two ? rowb : row;
;         f32x4 ha[4], hb[4]; v2u ya[4], yb[4];
;         { const f32x4* hr = (const f32x4*)(hin + (size_t)row * DM) + lane; const f32x4* hr2 = (const f32x4*)(hin + (size_t)rb * DM) + lane;
; #pragma unroll
;           for (int j = 0; j < 4; ++j) { ha[j] = hr[64 * j]; hb[j] = hr2[64 * j]; }
;     ...
;                 for (int j = 0; j < 4; ++j) { const f32x4 g = *((const f32x4*)g_post + lane + 64 * j); h[j] = h[j] + y[j] * g * rinv; }
;             }
;             f32x4* ho = (f32x4*)(hout + (size_t)r * DM) + lane;
; #pragma unroll
;             for (int j = 0; j < 4; ++j) ho[64 * j] = h[j];
;             if (g_pre) {
;                 float s = 0.f;
; #pragma unroll
;                 for (int j = 0; j < 4; ++j) s += (h[j].x * h[j].x + h[j].y * h[j].y) + (h[j].z * h[j].z + h[j].w * h[j].w);
;                 const float rinv = rsqrtf(wave_sum(s) * (1.f / DM) + NORM_EPS);
;                 unsigned long long* o8 = (unsigned long long*)(xn + (size_t)r * DM) + lane;
; #pragma unroll
;                 for (int j = 0; j < 4; ++j) { const f32x4 g = *((const f32x4*)g_pre + lane + 64 * j); const f32x4 v = h[j] * g * rinv;
.LBB0_1359:
	s_mov_b32 s4, s50
	s_mov_b32 s5, s51
	s_mov_b32 s14, s50
	s_mov_b32 s15, s51
	v_mov_b32_e32 v0, v185
	s_nop 0
	v_readfirstlane_b32 s6, v0
	s_ashr_i32 s8, s6, 6
	v_readlane_b32 s6, v253, 7
	s_add_i32 s18, s8, s6
	s_cmpk_gt_i32 s18, 0x3fff
	s_cbranch_scc1 .LBB0_1367
	v_and_b32_e32 v2, 63, v0
	v_lshlrev_b32_e32 v36, 3, v2
	v_mov_b32_e32 v37, v1
	v_lshlrev_b32_e32 v0, 4, v2
	v_lshl_add_u64 v[2:3], s[4:5], 0, v[36:37]
	s_mov_b64 s[6:7], 0x12e00000
	v_lshl_add_u64 v[38:39], v[2:3], 0, s[6:7]
	v_readlane_b32 s6, v255, 9
	v_readlane_b32 s7, v255, 10
	v_and_b32_e32 v2, 64, v241
	v_add_u32_e32 v2, 64, v2
	v_lshl_add_u64 v[40:41], s[6:7], 0, v[0:1]
	v_readlane_b32 s6, v255, 7
	v_readlane_b32 s7, v255, 8
	v_xor_b32_e32 v3, 1, v241
	v_cmp_lt_i32_e32 vcc, v3, v2
	v_lshl_add_u64 v[42:43], s[6:7], 0, v[0:1]
	s_ashr_i32 s6, s8, 31
	v_readlane_b32 s7, v253, 7
	s_add_u32 s10, s7, s8
	v_readlane_b32 s7, v253, 6
	s_addc_u32 s11, s7, s6
	v_cndmask_b32_e32 v3, v241, v3, vcc
	s_lshl_b64 s[6:7], s[10:11], 12
	v_lshlrev_b32_e32 v72, 2, v3
	v_xor_b32_e32 v3, 2, v241
	s_add_u32 s6, s48, s6
	v_readlane_b32 s9, v253, 8
	v_cmp_lt_i32_e32 vcc, v3, v2
	s_addc_u32 s7, s49, s7
	s_add_i32 s12, s9, s8
	v_cndmask_b32_e32 v3, v241, v3, vcc
	s_ashr_i32 s13, s12, 31
	v_lshlrev_b32_e32 v73, 2, v3
	v_xor_b32_e32 v3, 4, v241
	s_lshl_b64 s[8:9], s[12:13], 11
	v_cmp_lt_i32_e32 vcc, v3, v2
	s_add_u32 s8, s14, s8
	s_addc_u32 s9, s15, s9
	v_cndmask_b32_e32 v3, v241, v3, vcc
	s_lshl_b64 s[16:17], s[10:11], 11
	v_lshlrev_b32_e32 v74, 2, v3
	v_xor_b32_e32 v3, 8, v241
	s_add_u32 s4, s4, s16
	v_cmp_lt_i32_e32 vcc, v3, v2
	s_addc_u32 s5, s5, s17
	s_add_u32 s10, s4, 0x12e00400
	v_cndmask_b32_e32 v3, v241, v3, vcc
	v_lshlrev_b32_e32 v75, 2, v3
	v_xor_b32_e32 v3, 16, v241
	s_addc_u32 s11, s5, 0
	s_lshl_b64 s[4:5], s[12:13], 12
	v_cmp_lt_i32_e32 vcc, v3, v2
	s_add_u32 s12, s48, s4
	s_addc_u32 s13, s49, s5
	v_cndmask_b32_e32 v3, v241, v3, vcc
	v_lshlrev_b32_e32 v76, 2, v3
	v_xor_b32_e32 v3, 32, v241
	s_add_u32 s4, s14, s16
	v_cmp_lt_i32_e32 vcc, v3, v2
	s_addc_u32 s5, s15, s17
	s_add_u32 s14, s4, 0x16e00400
	v_cndmask_b32_e32 v2, v241, v3, vcc
	v_lshl_add_u64 v[34:35], s[48:49], 0, v[0:1]
	v_lshlrev_b32_e32 v77, 2, v2
	s_addc_u32 s15, s5, 0
	global_load_dwordx4 v[140:143], v[40:41], off
	global_load_dwordx4 v[144:147], v[40:41], off offset:1024
	global_load_dwordx4 v[148:151], v[40:41], off offset:2048
	global_load_dwordx4 v[152:155], v[40:41], off offset:3072
	v_readlane_b32 s20, v255, 5
	v_readlane_b32 s21, v255, 6
	s_nop 3
	s_andn2_b64 vcc, exec, s[20:21]
	s_cbranch_vccnz .Lrw_nopre_2
	global_load_dwordx4 v[156:159], v[42:43], off
	global_load_dwordx4 v[160:163], v[42:43], off offset:1024
	global_load_dwordx4 v[164:167], v[42:43], off offset:2048
	global_load_dwordx4 v[168:171], v[42:43], off offset:3072

; __device__ __forceinline__ float bflo(unsigned w) { return __uint_as_float(w << 16); }
; __device__ __forceinline__ float bfhi(unsigned w) { return __uint_as_float(w & 0xffff0000u); }
; __device__ __forceinline__ float bflo(unsigned w) { return __uint_as_float(w << 16); }
; __device__ __forceinline__ float bfhi(unsigned w) { return __uint_as_float(w & 0xffff0000u); }
; __device__ __forceinline__ void phase_rowwise(const bf16_t* ysrc, const float* hin, float* hout, float wt, const float* g_post, const float* g_pre, bf16_t* xn) {
;     ...
;     for (int row = gw; row < T; row += 2 * ngw) {
;         const int rowb = row + ngw; const bool two = rowb < T; const int rb = two ? rowb : row;
;         f32x4 ha[4], hb[4]; v2u ya[4], yb[4];
;         { const f32x4* hr = (const f32x4*)(hin + (size_t)row * DM) + lane; const f32x4* hr2 = (const f32x4*)(hin + (size_t)rb * DM) + lane;
; #pragma unroll
;           for (int j = 0; j < 4; ++j) { ha[j] = hr[64 * j]; hb[j] = hr2[64 * j]; }
;           if (ysrc) { const v2u* yr = (const v2u*)(ysrc + (size_t)row * DM) + lane; const v2u* yr2 = (const v2u*)(ysrc + (size_t)rb * DM) + lane;
; #pragma unroll
;             for (int j = 0; j < 4; ++j) { ya[j] = yr[64 * j]; yb[j] = yr2[64 * j]; } } }
; #pragma unroll
;         for (int half = 0; half < 2; ++half) {
;             if (half == 1 && !two) break;
;             const int r = half ? rowb : row;
;             f32x4 h[4];
; #pragma unroll
;             for (int j = 0; j < 4; ++j) h[j] = half ? hb[j] : ha[j];
;             if (ysrc) {
;                 f32x4 y[4]; float s = 0.f;
; #pragma unroll
;                 for (int j = 0; j < 4; ++j) { const v2u w = half ? yb[j] : ya[j]; y[j] = (f32x4){bflo(w.x), bfhi(w.x), bflo(w.y), bfhi(w.y)}; s += (y[j].x * y[j].x + y[j].y * y[j].y) + (y[j].z * y[j].z + y[j].w * y[j].w); }
;                 const float rinv = wt * rsqrtf(wave_sum(s) * (1.f / DM) + NORM_EPS);
; #pragma unroll
;                 for (int j = 0; j < 4; ++j) { const f32x4 g = *((const f32x4*)g_post + lane + 64 * j); h[j] = h[j] + y[j] * g * rinv; }
;             }
;             f32x4* ho = (f32x4*)(hout + (size_t)r * DM) + lane;
; #pragma unroll
;             for (int j = 0; j < 4; ++j) ho[64 * j] = h[j];
.LBB0_1362:
	s_add_i32 s19, s24, s18
	s_cmpk_lt_i32 s19, 0x4000
	s_cselect_b64 s[16:17], -1, 0
	s_and_b64 s[4:5], s[16:17], exec
	s_cselect_b32 s4, s19, s18
	s_ashr_i32 s5, s4, 31
	s_lshl_b64 s[20:21], s[4:5], 12
	v_lshl_add_u64 v[52:53], s[6:7], 0, v[0:1]
	v_lshl_add_u64 v[2:3], v[34:35], 0, s[20:21]
	v_lshl_add_u64 v[48:49], s[10:11], 0, v[36:37]
	s_lshl_b64 s[4:5], s[4:5], 11
	global_load_dwordx4 v[18:21], v[52:53], off
	global_load_dwordx4 v[14:17], v[2:3], off
	global_load_dwordx4 v[22:25], v[52:53], off offset:1024
	global_load_dwordx4 v[10:13], v[2:3], off offset:1024
	global_load_dwordx4 v[26:29], v[52:53], off offset:2048
	global_load_dwordx4 v[6:9], v[2:3], off offset:2048
	global_load_dwordx4 v[30:33], v[52:53], off offset:3072
	s_nop 0
	global_load_dwordx4 v[2:5], v[2:3], off offset:3072
	v_lshl_add_u64 v[54:55], v[38:39], 0, s[4:5]
	global_load_dwordx2 v[56:57], v[48:49], off offset:-1024
	global_load_dwordx2 v[50:51], v[54:55], off
	global_load_dwordx2 v[58:59], v[48:49], off offset:-512
	global_load_dwordx2 v[46:47], v[54:55], off offset:512
	global_load_dwordx2 v[62:63], v[48:49], off
	global_load_dwordx2 v[44:45], v[54:55], off offset:1024
	global_load_dwordx2 v[78:79], v[48:49], off offset:512
	s_nop 0
	global_load_dwordx2 v[48:49], v[54:55], off offset:1536
	v_readlane_b32 s20, v255, 5
	v_readlane_b32 s21, v255, 6
	s_waitcnt vmcnt(7)
	v_and_b32_e32 v71, 0xffff0000, v57
	v_and_b32_e32 v69, 0xffff0000, v56
	v_lshlrev_b32_e32 v70, 16, v57
	v_mul_f32_e32 v54, v71, v71
	s_waitcnt vmcnt(5)
	v_and_b32_e32 v67, 0xffff0000, v59
	v_and_b32_e32 v66, 0xffff0000, v58
	v_lshlrev_b32_e32 v68, 16, v56
	v_pk_fma_f32 v[80:81], v[70:71], v[70:71], v[54:55] op_sel_hi:[1,1,0]
	v_lshlrev_b32_e32 v65, 16, v59
	v_lshlrev_b32_e32 v64, 16, v58
	v_pk_mul_f32 v[54:55], v[66:67], v[66:67]
	s_waitcnt vmcnt(1)
	v_and_b32_e32 v57, 0xffff0000, v78
	v_mul_f32_e32 v56, v69, v69
	v_pk_fma_f32 v[82:83], v[64:65], v[64:65], v[54:55]
	v_lshlrev_b32_e32 v59, 16, v78
	v_lshlrev_b32_e32 v54, 16, v79
	v_and_b32_e32 v55, 0xffff0000, v79
	v_pk_fma_f32 v[78:79], v[68:69], v[68:69], v[56:57] op_sel_hi:[1,1,0]
	v_mov_b32_e32 v84, v80
	v_mov_b32_e32 v58, v78
	v_mov_b32_e32 v85, v59
	v_pk_add_f32 v[78:79], v[78:79], v[80:81]
	v_pk_mul_f32 v[80:81], v[58:59], v[84:85]
	v_and_b32_e32 v61, 0xffff0000, v62
	v_mul_f32_e32 v86, v57, v57
	v_mov_b32_e32 v79, v81
	v_pk_add_f32 v[80:81], v[82:83], v[82:83] op_sel:[0,1] op_sel_hi:[1,0]
	v_lshlrev_b32_e32 v60, 16, v62
	v_lshlrev_b32_e32 v62, 16, v63
	v_and_b32_e32 v63, 0xffff0000, v63
	v_mov_b32_e32 v81, v86
	v_mul_f32_e32 v56, v61, v61
	v_pk_add_f32 v[78:79], v[78:79], v[80:81]
	v_pk_fma_f32 v[80:81], v[60:61], v[60:61], v[56:57] op_sel_hi:[1,1,0]
	v_mul_f32_e32 v56, v63, v63
	v_mul_f32_e32 v87, v54, v54
	v_mul_f32_e32 v88, v55, v55
	v_pk_fma_f32 v[82:83], v[62:63], v[62:63], v[56:57] op_sel_hi:[1,1,0]
	v_mov_b32_e32 v81, v87
	v_mov_b32_e32 v83, v88
	v_pk_add_f32 v[80:81], v[80:81], v[82:83]
	s_nop 0
	v_pk_add_f32 v[78:79], v[78:79], v[80:81]
	s_nop 0
	v_add_f32_e32 v56, v78, v79
	v_mov_b64_e32 v[78:79], v[140:141]
	v_mov_b64_e32 v[80:81], v[142:143]
	ds_bpermute_b32 v58, v72, v56
	s_waitcnt lgkmcnt(0)
	v_add_f32_e32 v56, v56, v58
	ds_bpermute_b32 v58, v73, v56
	s_waitcnt lgkmcnt(0)
	v_add_f32_e32 v56, v56, v58
	ds_bpermute_b32 v58, v74, v56
	s_waitcnt lgkmcnt(0)
	v_add_f32_e32 v56, v56, v58
	ds_bpermute_b32 v58, v75, v56
	s_waitcnt lgkmcnt(0)
	v_add_f32_e32 v56, v56, v58
	ds_bpermute_b32 v58, v76, v56
	s_waitcnt lgkmcnt(0)
	v_add_f32_e32 v56, v56, v58
	ds_bpermute_b32 v58, v77, v56
	s_waitcnt lgkmcnt(0)
	v_add_f32_e32 v56, v56, v58
	v_fmamk_f32 v56, v56, 0x3a800000, v184
	v_cmp_gt_f32_e32 vcc, s61, v56
	v_mul_f32_e32 v58, 0x4b800000, v56
	s_waitcnt vmcnt(0)
	v_pk_mul_f32 v[68:69], v[78:79], v[68:69]
	v_cndmask_b32_e32 v56, v56, v58, vcc
	v_rsq_f32_e32 v56, v56
	v_pk_mul_f32 v[70:71], v[80:81], v[70:71]
	v_mov_b32_e32 v79, v66
	v_mov_b32_e32 v66, v65
	v_mul_f32_e32 v58, 0x45800000, v56
	v_cndmask_b32_e32 v56, v56, v58, vcc
	v_mul_f32_e32 v58, 0.5, v56
	v_pk_fma_f32 v[20:21], v[70:71], v[58:59], v[20:21] op_sel_hi:[1,0,1]
	v_pk_fma_f32 v[18:19], v[68:69], v[58:59], v[18:19] op_sel_hi:[1,0,1]
	v_mov_b64_e32 v[68:69], v[144:145]
	v_mov_b64_e32 v[70:71], v[146:147]
	v_mov_b32_e32 v78, v64
	v_mov_b32_e32 v56, v59
	s_andn2_b64 vcc, exec, s[20:21]
	v_pk_mul_f32 v[64:65], v[70:71], v[66:67]
	s_nop 0
	v_pk_fma_f32 v[24:25], v[64:65], v[58:59], v[24:25] op_sel_hi:[1,0,1]
	v_mov_b64_e32 v[64:65], v[148:149]
	v_mov_b64_e32 v[66:67], v[150:151]
	v_pk_mul_f32 v[68:69], v[68:69], v[78:79]
	v_pk_mul_f32 v[60:61], v[64:65], v[60:61]
	v_pk_mul_f32 v[62:63], v[66:67], v[62:63]
	v_pk_fma_f32 v[26:27], v[60:61], v[58:59], v[26:27] op_sel_hi:[1,0,1]
	v_pk_fma_f32 v[28:29], v[62:63], v[58:59], v[28:29] op_sel_hi:[1,0,1]
	v_mov_b64_e32 v[60:61], v[152:153]
	v_mov_b64_e32 v[62:63], v[154:155]
	v_pk_fma_f32 v[22:23], v[68:69], v[58:59], v[22:23] op_sel_hi:[1,0,1]
	v_pk_mul_f32 v[56:57], v[56:57], v[60:61]
	v_pk_mul_f32 v[54:55], v[54:55], v[62:63]
	v_pk_fma_f32 v[30:31], v[56:57], v[58:59], v[30:31] op_sel_hi:[1,0,1]
	v_pk_fma_f32 v[32:33], v[54:55], v[58:59], v[32:33] op_sel_hi:[1,0,1]
	global_store_dwordx4 v[52:53], v[18:21], off
	global_store_dwordx4 v[52:53], v[22:25], off offset:1024
	global_store_dwordx4 v[52:53], v[26:29], off offset:2048
	global_store_dwordx4 v[52:53], v[30:33], off offset:3072
	v_cndmask_b32_e64 v52, 0, 1, s[20:21]
	v_cmp_ne_u32_e64 s[4:5], 1, v52
	s_cbranch_vccnz .LBB0_1364
; __device__ __forceinline__ unsigned pk2(float lo, float hi) { f32x2_t v = {lo, hi}; bf16x2_t b = __builtin_convertvector(v, bf16x2_t); return __builtin_bit_cast(unsigned, b); }
; __device__ __forceinline__ void phase_rowwise(const bf16_t* ysrc, const float* hin, float* hout, float wt, const float* g_post, const float* g_pre, bf16_t* xn) {
;     ...
;             if (g_pre) {
;                 float s = 0.f;
; #pragma unroll
;                 for (int j = 0; j < 4; ++j) s += (h[j].x * h[j].x + h[j].y * h[j].y) + (h[j].z * h[j].z + h[j].w * h[j].w);
;                 const float rinv = rsqrtf(wave_sum(s) * (1.f / DM) + NORM_EPS);
;                 unsigned long long* o8 = (unsigned long long*)(xn + (size_t)r * DM) + lane;
; #pragma unroll
;                 for (int j = 0; j < 4; ++j) { const f32x4 g = *((const f32x4*)g_pre + lane + 64 * j); const f32x4 v = h[j] * g * rinv;
;                     o8[64 * j] = (unsigned long long)pk2(v.x, v.y) | ((unsigned long long)pk2(v.z, v.w) << 32); }
	v_pk_mul_f32 v[52:53], v[20:21], v[20:21]
	v_pk_mul_f32 v[54:55], v[18:19], v[18:19]
	s_nop 0
	v_pk_mov_b32 v[56:57], v[54:55], v[52:53] op_sel:[1,0]
	v_mov_b32_e32 v55, v53
	v_pk_add_f32 v[52:53], v[56:57], v[54:55]
	v_pk_mul_f32 v[54:55], v[24:25], v[24:25]
	v_pk_add_f32 v[52:53], v[52:53], v[52:53] op_sel_hi:[0,1]
	v_pk_mul_f32 v[56:57], v[22:23], v[22:23]
	v_mul_f32_e32 v52, v26, v26
	v_pk_mov_b32 v[58:59], v[56:57], v[54:55] op_sel:[1,0]
	v_mov_b32_e32 v57, v55
	v_pk_add_f32 v[54:55], v[58:59], v[56:57]
	v_pk_fma_f32 v[56:57], v[26:27], v[26:27], v[52:53] op_sel_hi:[1,1,0]
	v_mul_f32_e32 v52, v28, v28
	v_pk_add_f32 v[54:55], v[54:55], v[54:55] op_sel_hi:[0,1]
	v_pk_fma_f32 v[58:59], v[28:29], v[28:29], v[52:53] op_sel_hi:[1,1,0]
	v_mul_f32_e32 v56, v30, v30
	v_mul_f32_e32 v58, v31, v31
	v_mul_f32_e32 v52, v32, v32
	v_mul_f32_e32 v54, v33, v33
	v_pk_add_f32 v[56:57], v[56:57], v[58:59]
	v_pk_add_f32 v[52:53], v[52:53], v[54:55]
	s_nop 0
	v_pk_add_f32 v[52:53], v[56:57], v[52:53]
	v_mov_b64_e32 v[56:57], v[156:157]
	v_mov_b64_e32 v[58:59], v[158:159]
	v_add_f32_e32 v52, v52, v53
	ds_bpermute_b32 v53, v72, v52
	s_waitcnt lgkmcnt(0)
	v_add_f32_e32 v52, v52, v53
	ds_bpermute_b32 v53, v73, v52
	s_waitcnt lgkmcnt(0)
	v_add_f32_e32 v52, v52, v53
	ds_bpermute_b32 v53, v74, v52
	s_waitcnt lgkmcnt(0)
	v_add_f32_e32 v52, v52, v53
	ds_bpermute_b32 v53, v75, v52
	s_waitcnt lgkmcnt(0)
	v_add_f32_e32 v52, v52, v53
	ds_bpermute_b32 v53, v76, v52
	s_waitcnt lgkmcnt(0)
	v_add_f32_e32 v52, v52, v53
	ds_bpermute_b32 v53, v77, v52
	s_waitcnt lgkmcnt(0)
	v_add_f32_e32 v52, v52, v53
	v_fmamk_f32 v52, v52, 0x3a800000, v184
	v_cmp_gt_f32_e32 vcc, s61, v52
	v_mul_f32_e32 v53, 0x4b800000, v52
	v_pk_mul_f32 v[20:21], v[20:21], v[58:59]
	v_cndmask_b32_e32 v52, v52, v53, vcc
	v_rsq_f32_e32 v52, v52
	v_pk_mul_f32 v[18:19], v[18:19], v[56:57]
	v_mul_f32_e32 v53, 0x45800000, v52
	v_cndmask_b32_e32 v54, v52, v53, vcc
	v_pk_mul_f32 v[20:21], v[20:21], v[54:55] op_sel_hi:[1,0]
	v_pk_mul_f32 v[18:19], v[18:19], v[54:55] op_sel_hi:[1,0]
	v_lshl_add_u64 v[52:53], s[14:15], 0, v[36:37]
	v_cvt_pk_bf16_f32 v18, v18, v19
	v_cvt_pk_bf16_f32 v19, v20, v21
	global_store_dwordx2 v[52:53], v[18:19], off offset:-1024
	v_mov_b64_e32 v[18:19], v[160:161]
	v_mov_b64_e32 v[20:21], v[162:163]
	v_pk_mul_f32 v[20:21], v[24:25], v[20:21]
	v_pk_mul_f32 v[18:19], v[22:23], v[18:19]
	v_pk_mul_f32 v[20:21], v[20:21], v[54:55] op_sel_hi:[1,0]
	v_pk_mul_f32 v[18:19], v[18:19], v[54:55] op_sel_hi:[1,0]
	s_nop 0
	v_cvt_pk_bf16_f32 v18, v18, v19
	v_cvt_pk_bf16_f32 v19, v20, v21
	global_store_dwordx2 v[52:53], v[18:19], off offset:-512
	v_mov_b64_e32 v[18:19], v[164:165]
	v_mov_b64_e32 v[20:21], v[166:167]
	v_pk_mul_f32 v[20:21], v[28:29], v[20:21]
	v_pk_mul_f32 v[18:19], v[26:27], v[18:19]
	v_pk_mul_f32 v[20:21], v[20:21], v[54:55] op_sel_hi:[1,0]
	v_pk_mul_f32 v[18:19], v[18:19], v[54:55] op_sel_hi:[1,0]
	s_nop 0
	v_cvt_pk_bf16_f32 v18, v18, v19
	v_cvt_pk_bf16_f32 v19, v20, v21
	global_store_dwordx2 v[52:53], v[18:19], off
	v_mov_b64_e32 v[18:19], v[168:169]
	v_mov_b64_e32 v[20:21], v[170:171]
	v_pk_mul_f32 v[20:21], v[32:33], v[20:21]
	v_pk_mul_f32 v[18:19], v[30:31], v[18:19]
	v_pk_mul_f32 v[20:21], v[20:21], v[54:55] op_sel_hi:[1,0]
	v_pk_mul_f32 v[18:19], v[18:19], v[54:55] op_sel_hi:[1,0]
	s_nop 0
	v_cvt_pk_bf16_f32 v18, v18, v19
	v_cvt_pk_bf16_f32 v19, v20, v21
	global_store_dwordx2 v[52:53], v[18:19], off offset:512
